# extra wait states after 128-bit stores before VALU overwrites of their data registers (GEMM2 epilogue, post phase); otherwise as previous best
# speedup vs baseline: 1.0116x; 1.0030x over previous
; __device__ __forceinline__ float bflo(unsigned w) { return __uint_as_float(w << 16); }
; __device__ __forceinline__ float bfhi(unsigned w) { return __uint_as_float(w & 0xFFFF0000u); }
; __device__ __forceinline__ float siluf(float v) { return v * __builtin_amdgcn_rcpf(1.f + __expf(-v)); }
; __device__ void phase_post(const Params& p, int l) {
;     ...
;         {
;             float tv[32]; float ss = 0.f;
; #pragma unroll
;             for (int q = 0; q < 4; ++q) { const u32x4 yv = *(const u32x4*)(pr + 8192 + c0 + q * 8), zv = *(const u32x4*)(pr + 11264 + c0 + q * 8), yb = *(const u32x4*)(p.YB + (size_t)row * 2048 + c0 + q * 8);
; #pragma unroll
;                 for (int e = 0; e < 4; ++e) { const float t0 = (bflo(yv[e]) + bflo(yb[e])) * siluf(bflo(zv[e])), t1 = (bfhi(yv[e]) + bfhi(yb[e])) * siluf(bfhi(zv[e]));
;                     tv[q * 8 + 2 * e] = t0; tv[q * 8 + 2 * e + 1] = t1; ss += t0 * t0 + t1 * t1; } }
;             const float rstd = rsqrtf(wsum(ss) * (1.f / 2048.f) + LN_EPS);
.LBB0_12:
	v_lshl_add_u64 v[46:47], v[38:39], 0, v[148:149]
	v_add_co_u32_e32 v44, vcc, 0x8a04000, v46
	s_mov_b64 s[4:5], 0x8a04000
	s_nop 0
	v_addc_co_u32_e32 v45, vcc, 0, v47, vcc
	s_mov_b32 s3, 0x8a05000
	v_lshl_add_u64 v[4:5], v[46:47], 0, s[4:5]
	s_mov_b64 s[4:5], 0x8a05800
	v_add_co_u32_e32 v48, vcc, s3, v46
	v_lshl_add_u64 v[6:7], v[46:47], 0, s[4:5]
	v_lshl_add_u64 v[8:9], v[40:41], 0, v[148:149]
	v_addc_co_u32_e32 v49, vcc, 0, v47, vcc
	global_load_dwordx4 v[58:61], v[44:45], off
	global_load_dwordx4 v[0:3], v[4:5], off offset:48
	global_load_dwordx4 v[20:23], v[4:5], off offset:32
	global_load_dwordx4 v[66:69], v[4:5], off offset:16
	global_load_dwordx4 v[70:73], v[48:49], off offset:2048
	global_load_dwordx4 v[12:15], v[6:7], off offset:48
	global_load_dwordx4 v[28:31], v[6:7], off offset:32
	global_load_dwordx4 v[74:77], v[6:7], off offset:16
	s_nop 0
	global_load_dwordx4 v[4:7], v[8:9], off offset:48
	global_load_dwordx4 v[24:27], v[8:9], off offset:32
	global_load_dwordx4 v[78:81], v[8:9], off offset:16
	global_load_dwordx4 v[82:85], v[8:9], off
	s_nop 0
	s_mov_b32 s3, 0x8a00000
	s_mov_b64 s[4:5], 0x8a00000
	v_add_u32_e32 v32, s8, v32
	v_lshl_add_u64 v[38:39], v[38:39], 0, s[10:11]
	v_lshl_add_u64 v[40:41], v[40:41], 0, s[12:13]
	v_mov_b64_e32 v[8:9], v[164:165]
	v_mov_b64_e32 v[10:11], v[166:167]
	v_mov_b64_e32 v[16:17], v[160:161]
	v_mov_b64_e32 v[18:19], v[162:163]
	s_waitcnt vmcnt(7)
	v_lshlrev_b32_e32 v50, 16, v73
	v_mul_f32_e32 v33, 0xbfb8aa3b, v50
	v_exp_f32_e32 v33, v33
	v_and_b32_e32 v51, 0xffff0000, v73
	s_waitcnt vmcnt(3)
	v_lshlrev_b32_e32 v92, 16, v7
	v_lshlrev_b32_e32 v54, 16, v61
	v_add_f32_e32 v33, 1.0, v33
	v_rcp_f32_e32 v52, v33
	v_mul_f32_e32 v33, 0xbfb8aa3b, v51
	v_exp_f32_e32 v33, v33
	v_and_b32_e32 v55, 0xffff0000, v61
	s_waitcnt vmcnt(0)
	v_lshlrev_b32_e32 v56, 16, v85
	v_and_b32_e32 v57, 0xffff0000, v85
	v_add_f32_e32 v33, 1.0, v33
	v_rcp_f32_e32 v53, v33
	v_pk_add_f32 v[54:55], v[54:55], v[56:57]
	v_lshlrev_b32_e32 v62, 16, v60
	v_and_b32_e32 v63, 0xffff0000, v60
	v_pk_mul_f32 v[50:51], v[52:53], v[50:51]
	v_lshlrev_b32_e32 v52, 16, v72
	v_mul_f32_e32 v33, 0xbfb8aa3b, v52
	v_exp_f32_e32 v33, v33
	v_and_b32_e32 v53, 0xffff0000, v72
	v_pk_mul_f32 v[50:51], v[54:55], v[50:51]
	v_lshlrev_b32_e32 v60, 16, v84
	v_add_f32_e32 v33, 1.0, v33
	v_rcp_f32_e32 v54, v33
	v_mul_f32_e32 v33, 0xbfb8aa3b, v53
	v_exp_f32_e32 v33, v33
	v_and_b32_e32 v61, 0xffff0000, v84
	v_pk_add_f32 v[60:61], v[62:63], v[60:61]
	v_lshlrev_b32_e32 v64, 16, v59
	v_add_f32_e32 v33, 1.0, v33
	v_rcp_f32_e32 v55, v33
	v_and_b32_e32 v65, 0xffff0000, v59
	v_lshlrev_b32_e32 v72, 16, v83
	v_and_b32_e32 v73, 0xffff0000, v83
	v_pk_mul_f32 v[52:53], v[54:55], v[52:53]
	v_lshlrev_b32_e32 v54, 16, v71
	v_mul_f32_e32 v33, 0xbfb8aa3b, v54
	v_exp_f32_e32 v33, v33
	v_and_b32_e32 v55, 0xffff0000, v71
	v_pk_mul_f32 v[52:53], v[60:61], v[52:53]
	v_pk_add_f32 v[64:65], v[64:65], v[72:73]
	v_add_f32_e32 v33, 1.0, v33
	v_rcp_f32_e32 v60, v33
	v_mul_f32_e32 v33, 0xbfb8aa3b, v55
	v_exp_f32_e32 v33, v33
	v_and_b32_e32 v71, 0xffff0000, v58
	v_and_b32_e32 v59, 0xffff0000, v82
	v_and_b32_e32 v83, 0xffff0000, v69
	v_add_f32_e32 v33, 1.0, v33
	v_rcp_f32_e32 v61, v33
	v_lshlrev_b32_e32 v84, 16, v81
	v_and_b32_e32 v85, 0xffff0000, v81
	v_lshlrev_b32_e32 v86, 16, v79
	v_pk_mul_f32 v[54:55], v[60:61], v[54:55]
	v_lshlrev_b32_e32 v60, 16, v70
	v_mul_f32_e32 v33, 0xbfb8aa3b, v60
	v_exp_f32_e32 v33, v33
	v_and_b32_e32 v61, 0xffff0000, v70
	v_pk_mul_f32 v[54:55], v[64:65], v[54:55]
	v_lshlrev_b32_e32 v70, 16, v58
	v_add_f32_e32 v33, 1.0, v33
	v_rcp_f32_e32 v64, v33
	v_mul_f32_e32 v33, 0xbfb8aa3b, v61
	v_exp_f32_e32 v33, v33
	v_lshlrev_b32_e32 v58, 16, v82
	v_pk_add_f32 v[58:59], v[70:71], v[58:59]
	v_lshlrev_b32_e32 v82, 16, v69
	v_add_f32_e32 v33, 1.0, v33
	v_rcp_f32_e32 v65, v33
	v_pk_add_f32 v[82:83], v[82:83], v[84:85]
	v_lshlrev_b32_e32 v84, 16, v68
	v_and_b32_e32 v85, 0xffff0000, v68
	v_pk_mul_f32 v[60:61], v[64:65], v[60:61]
	v_lshlrev_b32_e32 v68, 16, v80
	v_pk_mul_f32 v[60:61], v[58:59], v[60:61]
	v_lshlrev_b32_e32 v58, 16, v77
	v_mul_f32_e32 v33, 0xbfb8aa3b, v58
	v_exp_f32_e32 v33, v33
	v_and_b32_e32 v59, 0xffff0000, v77
	v_and_b32_e32 v69, 0xffff0000, v80
	v_pk_add_f32 v[68:69], v[84:85], v[68:69]
	v_add_f32_e32 v33, 1.0, v33
	v_rcp_f32_e32 v64, v33
	v_mul_f32_e32 v33, 0xbfb8aa3b, v59
	v_exp_f32_e32 v33, v33
	v_lshlrev_b32_e32 v84, 16, v67
	v_and_b32_e32 v85, 0xffff0000, v67
	v_and_b32_e32 v87, 0xffff0000, v79
	v_add_f32_e32 v33, 1.0, v33
	v_rcp_f32_e32 v65, v33
	v_pk_add_f32 v[84:85], v[84:85], v[86:87]
	v_lshlrev_b32_e32 v86, 16, v66
	v_and_b32_e32 v87, 0xffff0000, v66
	v_pk_mul_f32 v[58:59], v[64:65], v[58:59]
	v_lshlrev_b32_e32 v64, 16, v76
	v_mul_f32_e32 v33, 0xbfb8aa3b, v64
	v_exp_f32_e32 v33, v33
	v_and_b32_e32 v65, 0xffff0000, v76
	v_lshlrev_b32_e32 v66, 16, v78
	v_and_b32_e32 v67, 0xffff0000, v78
	v_add_f32_e32 v33, 1.0, v33
	v_rcp_f32_e32 v76, v33
	v_mul_f32_e32 v33, 0xbfb8aa3b, v65
	v_exp_f32_e32 v33, v33
	v_lshlrev_b32_e32 v78, 16, v31
	v_and_b32_e32 v79, 0xffff0000, v31
	v_pk_add_f32 v[66:67], v[86:87], v[66:67]
	v_add_f32_e32 v33, 1.0, v33
	v_rcp_f32_e32 v77, v33
	v_mul_f32_e32 v31, 0xbfb8aa3b, v78
	v_lshlrev_b32_e32 v86, 16, v23
	v_and_b32_e32 v87, 0xffff0000, v23
	v_pk_mul_f32 v[64:65], v[76:77], v[64:65]
	v_lshlrev_b32_e32 v76, 16, v75
	v_mul_f32_e32 v33, 0xbfb8aa3b, v76
	v_exp_f32_e32 v33, v33
	v_and_b32_e32 v77, 0xffff0000, v75
	v_mul_f32_e32 v23, 0xbfb8aa3b, v79
	v_exp_f32_e32 v31, v31
	v_add_f32_e32 v33, 1.0, v33
	v_rcp_f32_e32 v80, v33
	v_mul_f32_e32 v33, 0xbfb8aa3b, v77
	v_exp_f32_e32 v33, v33
	v_exp_f32_e32 v23, v23
	v_add_f32_e32 v31, 1.0, v31
; __device__ __forceinline__ float bflo(unsigned w) { return __uint_as_float(w << 16); }
; __device__ __forceinline__ float bfhi(unsigned w) { return __uint_as_float(w & 0xFFFF0000u); }
; __device__ __forceinline__ float siluf(float v) { return v * __builtin_amdgcn_rcpf(1.f + __expf(-v)); }
; __device__ void phase_post(const Params& p, int l) {
;     ...
;             for (int q = 0; q < 4; ++q) { const u32x4 yv = *(const u32x4*)(pr + 8192 + c0 + q * 8), zv = *(const u32x4*)(pr + 11264 + c0 + q * 8), yb = *(const u32x4*)(p.YB + (size_t)row * 2048 + c0 + q * 8);
; #pragma unroll
;                 for (int e = 0; e < 4; ++e) { const float t0 = (bflo(yv[e]) + bflo(yb[e])) * siluf(bflo(zv[e])), t1 = (bfhi(yv[e]) + bfhi(yb[e])) * siluf(bfhi(zv[e]));
;                     tv[q * 8 + 2 * e] = t0; tv[q * 8 + 2 * e + 1] = t1; ss += t0 * t0 + t1 * t1; } }
;             const float rstd = rsqrtf(wsum(ss) * (1.f / 2048.f) + LN_EPS);
	v_lshlrev_b32_e32 v88, 16, v27
	v_add_f32_e32 v33, 1.0, v33
	v_rcp_f32_e32 v81, v33
	v_add_f32_e32 v23, 1.0, v23
	v_and_b32_e32 v89, 0xffff0000, v27
	v_pk_add_f32 v[86:87], v[86:87], v[88:89]
	v_pk_mul_f32 v[76:77], v[80:81], v[76:77]
	v_lshlrev_b32_e32 v88, 16, v22
	v_pk_mul_f32 v[76:77], v[84:85], v[76:77]
	v_lshlrev_b32_e32 v84, 16, v74
	v_mul_f32_e32 v33, 0xbfb8aa3b, v84
	v_exp_f32_e32 v33, v33
	v_and_b32_e32 v85, 0xffff0000, v74
	v_and_b32_e32 v89, 0xffff0000, v22
	v_lshlrev_b32_e32 v22, 16, v26
	v_add_f32_e32 v33, 1.0, v33
	v_rcp_f32_e32 v74, v33
	v_mul_f32_e32 v33, 0xbfb8aa3b, v85
	v_exp_f32_e32 v33, v33
	v_lshlrev_b32_e32 v90, 16, v25
	v_and_b32_e32 v91, 0xffff0000, v25
	v_and_b32_e32 v93, 0xffff0000, v7
	v_add_f32_e32 v33, 1.0, v33
	v_rcp_f32_e32 v75, v33
	v_pk_mul_f32 v[72:73], v[54:55], v[54:55]
	v_pk_mul_f32 v[70:71], v[60:61], v[60:61]
	v_pk_mul_f32 v[62:63], v[52:53], v[52:53]
	v_pk_mul_f32 v[74:75], v[74:75], v[84:85]
	v_rcp_f32_e32 v84, v31
	v_rcp_f32_e32 v85, v23
	v_pk_mul_f32 v[56:57], v[50:51], v[50:51]
	v_pk_mul_f32 v[66:67], v[66:67], v[74:75]
	v_pk_mul_f32 v[64:65], v[68:69], v[64:65]
	v_pk_mul_f32 v[78:79], v[84:85], v[78:79]
	v_pk_mul_f32 v[74:75], v[66:67], v[66:67]
	v_pk_mul_f32 v[78:79], v[86:87], v[78:79]
	v_lshlrev_b32_e32 v86, 16, v30
	v_mul_f32_e32 v23, 0xbfb8aa3b, v86
	v_exp_f32_e32 v23, v23
	v_and_b32_e32 v87, 0xffff0000, v30
	v_pk_mul_f32 v[80:81], v[76:77], v[76:77]
	v_pk_mul_f32 v[58:59], v[82:83], v[58:59]
	v_add_f32_e32 v23, 1.0, v23
	v_rcp_f32_e32 v30, v23
	v_and_b32_e32 v23, 0xffff0000, v26
	v_mul_f32_e32 v26, 0xbfb8aa3b, v87
	v_exp_f32_e32 v26, v26
	v_pk_add_f32 v[22:23], v[88:89], v[22:23]
	v_lshlrev_b32_e32 v88, 16, v21
	v_and_b32_e32 v89, 0xffff0000, v21
	v_add_f32_e32 v26, 1.0, v26
	v_rcp_f32_e32 v31, v26
	v_pk_add_f32 v[88:89], v[88:89], v[90:91]
	v_lshlrev_b32_e32 v90, 16, v20
	v_and_b32_e32 v91, 0xffff0000, v20
	v_pk_mul_f32 v[26:27], v[30:31], v[86:87]
	v_lshlrev_b32_e32 v30, 16, v29
	v_and_b32_e32 v31, 0xffff0000, v29
	v_mul_f32_e32 v29, 0xbfb8aa3b, v30
	v_mul_f32_e32 v21, 0xbfb8aa3b, v31
	v_exp_f32_e32 v29, v29
	v_exp_f32_e32 v21, v21
	v_lshlrev_b32_e32 v20, 16, v24
	v_pk_mul_f32 v[68:69], v[64:65], v[64:65]
	v_add_f32_e32 v29, 1.0, v29
	v_add_f32_e32 v21, 1.0, v21
	v_rcp_f32_e32 v86, v29
	v_rcp_f32_e32 v87, v21
	v_pk_mul_f32 v[82:83], v[58:59], v[58:59]
	v_pk_mul_f32 v[22:23], v[22:23], v[26:27]
	v_pk_mul_f32 v[84:85], v[78:79], v[78:79]
	v_pk_mul_f32 v[30:31], v[86:87], v[30:31]
	v_pk_mul_f32 v[26:27], v[22:23], v[22:23]
	v_pk_mul_f32 v[30:31], v[88:89], v[30:31]
	v_lshlrev_b32_e32 v88, 16, v28
	v_mul_f32_e32 v21, 0xbfb8aa3b, v88
	v_exp_f32_e32 v21, v21
	v_and_b32_e32 v89, 0xffff0000, v28
	v_pk_mul_f32 v[86:87], v[30:31], v[30:31]
	v_add_f32_e32 v21, 1.0, v21
	v_rcp_f32_e32 v28, v21
	v_and_b32_e32 v21, 0xffff0000, v24
	v_mul_f32_e32 v24, 0xbfb8aa3b, v89
	v_exp_f32_e32 v24, v24
	v_pk_add_f32 v[20:21], v[90:91], v[20:21]
	v_lshlrev_b32_e32 v90, 16, v3
	v_and_b32_e32 v91, 0xffff0000, v3
	v_add_f32_e32 v24, 1.0, v24
	v_rcp_f32_e32 v29, v24
	v_pk_add_f32 v[90:91], v[90:91], v[92:93]
	v_lshlrev_b32_e32 v92, 16, v5
	v_and_b32_e32 v93, 0xffff0000, v5
	v_pk_mul_f32 v[24:25], v[28:29], v[88:89]
	v_lshlrev_b32_e32 v28, 16, v15
	v_and_b32_e32 v29, 0xffff0000, v15
	v_mul_f32_e32 v15, 0xbfb8aa3b, v28
	v_mul_f32_e32 v3, 0xbfb8aa3b, v29
	v_exp_f32_e32 v15, v15
	v_exp_f32_e32 v3, v3
	v_pk_mul_f32 v[20:21], v[20:21], v[24:25]
	v_add_f32_e32 v15, 1.0, v15
	v_add_f32_e32 v3, 1.0, v3
	v_rcp_f32_e32 v88, v15
	v_rcp_f32_e32 v89, v3
	v_pk_mul_f32 v[24:25], v[20:21], v[20:21]
	v_pk_mul_f32 v[28:29], v[88:89], v[28:29]
	v_lshlrev_b32_e32 v88, 16, v14
	v_mul_f32_e32 v3, 0xbfb8aa3b, v88
	v_exp_f32_e32 v3, v3
	v_and_b32_e32 v89, 0xffff0000, v14
	v_pk_mul_f32 v[28:29], v[90:91], v[28:29]
	v_lshlrev_b32_e32 v90, 16, v2
	v_add_f32_e32 v3, 1.0, v3
	v_rcp_f32_e32 v14, v3
	v_and_b32_e32 v91, 0xffff0000, v2
	v_lshlrev_b32_e32 v2, 16, v6
	v_and_b32_e32 v3, 0xffff0000, v6
	v_mul_f32_e32 v6, 0xbfb8aa3b, v89
	v_exp_f32_e32 v6, v6
	v_pk_add_f32 v[2:3], v[90:91], v[2:3]
	v_lshlrev_b32_e32 v90, 16, v1
	v_and_b32_e32 v91, 0xffff0000, v1
	v_add_f32_e32 v6, 1.0, v6
	v_rcp_f32_e32 v15, v6
	v_pk_add_f32 v[90:91], v[90:91], v[92:93]
	v_pk_mul_f32 v[6:7], v[14:15], v[88:89]
	s_nop 0
	v_pk_mul_f32 v[14:15], v[2:3], v[6:7]
	v_mov_b32_e32 v6, v29
	v_mov_b32_e32 v7, v15
	v_mov_b32_e32 v2, v28
	v_mov_b32_e32 v3, v14
	v_pk_mul_f32 v[6:7], v[6:7], v[6:7]
	s_nop 0
	v_pk_fma_f32 v[2:3], v[2:3], v[2:3], v[6:7]
	v_lshlrev_b32_e32 v6, 16, v13
	v_and_b32_e32 v7, 0xffff0000, v13
	v_mul_f32_e32 v13, 0xbfb8aa3b, v6
	v_mul_f32_e32 v1, 0xbfb8aa3b, v7
	v_exp_f32_e32 v13, v13
	v_exp_f32_e32 v1, v1
	v_add_f32_e32 v13, 1.0, v13
	v_add_f32_e32 v1, 1.0, v1
	v_rcp_f32_e32 v88, v13
	v_rcp_f32_e32 v89, v1
	s_nop 0
	v_pk_mul_f32 v[6:7], v[88:89], v[6:7]
	s_nop 0
	v_pk_mul_f32 v[88:89], v[90:91], v[6:7]
	v_lshlrev_b32_e32 v6, 16, v12
	v_mul_f32_e32 v1, 0xbfb8aa3b, v6
	v_exp_f32_e32 v1, v1
	v_and_b32_e32 v7, 0xffff0000, v12
	v_lshlrev_b32_e32 v90, 16, v0
	v_and_b32_e32 v91, 0xffff0000, v0
	v_add_f32_e32 v1, 1.0, v1
	v_rcp_f32_e32 v12, v1
	v_lshlrev_b32_e32 v0, 16, v4
	v_and_b32_e32 v1, 0xffff0000, v4
	v_mul_f32_e32 v4, 0xbfb8aa3b, v7
	v_exp_f32_e32 v4, v4
	v_pk_add_f32 v[0:1], v[90:91], v[0:1]
	v_add_f32_e32 v4, 1.0, v4
	v_rcp_f32_e32 v13, v4
	s_nop 0
	v_pk_mul_f32 v[4:5], v[12:13], v[6:7]
	s_nop 0
	v_pk_mul_f32 v[12:13], v[0:1], v[4:5]
	v_mov_b32_e32 v4, v89
	v_mov_b32_e32 v5, v13
	v_mov_b32_e32 v0, v88
	v_mov_b32_e32 v1, v12
	v_pk_mul_f32 v[4:5], v[4:5], v[4:5]
	s_nop 0
	v_pk_fma_f32 v[0:1], v[0:1], v[0:1], v[4:5]
	v_add_f32_e32 v4, v72, v73
	v_add_f32_e32 v5, v70, v71
	v_add_f32_e32 v4, v5, v4
	v_add_f32_e32 v5, v62, v63
	v_add_f32_e32 v4, v5, v4
	v_add_f32_e32 v5, v56, v57
	v_add_f32_e32 v4, v5, v4
	v_add_f32_e32 v5, v74, v75
	v_add_f32_e32 v4, v4, v5
	v_add_f32_e32 v5, v80, v81
	v_add_f32_e32 v4, v5, v4
	v_add_f32_e32 v5, v68, v69
	v_add_f32_e32 v4, v5, v4
	v_add_f32_e32 v5, v82, v83
	v_add_f32_e32 v4, v5, v4
	v_add_f32_e32 v5, v24, v25
	v_add_f32_e32 v4, v5, v4
	v_add_f32_e32 v5, v86, v87
	v_add_f32_e32 v4, v5, v4
	v_add_f32_e32 v5, v26, v27
	v_add_f32_e32 v4, v5, v4
	v_add_f32_e32 v5, v84, v85
	v_add_f32_e32 v4, v5, v4
	v_add_f32_e32 v1, v1, v4
	v_add_f32_e32 v0, v0, v1
	v_add_f32_e32 v0, v3, v0
	v_add_f32_e32 v0, v2, v0
	ds_bpermute_b32 v1, v112, v0
	s_waitcnt lgkmcnt(0)
; __device__ __forceinline__ unsigned pk2(float lo, float hi) { const f32x2_t v = {lo, hi}; return __builtin_bit_cast(unsigned, __builtin_convertvector(v, bf16x2_t)); }
; __device__ void phase_post(const Params& p, int l) {
;     ...
;             const float rstd = rsqrtf(wsum(ss) * (1.f / 2048.f) + LN_EPS);
;             const float* sw = p.ssm_w + (size_t)l * 2048 + c0;
; #pragma unroll
;             for (int q = 0; q < 4; ++q) { const f32x4 wa = *(const f32x4*)(sw + q * 8), wb = *(const f32x4*)(sw + q * 8 + 4);
;                 u32x4 o; o.x = pk2(tv[q * 8] * rstd * wa[0], tv[q * 8 + 1] * rstd * wa[1]); o.y = pk2(tv[q * 8 + 2] * rstd * wa[2], tv[q * 8 + 3] * rstd * wa[3]);
;                 o.z = pk2(tv[q * 8 + 4] * rstd * wb[0], tv[q * 8 + 5] * rstd * wb[1]); o.w = pk2(tv[q * 8 + 6] * rstd * wb[2], tv[q * 8 + 7] * rstd * wb[3]);
;                 *(u32x4*)(pr + 11264 + c0 + q * 8) = o; }
;         }
;         {
;             float hv[32]; float s = 0.f;
; #pragma unroll
;             for (int q = 0; q < 4; ++q) { const u32x4 a = *(const u32x4*)(pr + c0 + q * 8), ab = *(const u32x4*)(p.HB + (size_t)row * 2048 + c0 + q * 8);
	v_add_f32_e32 v0, v0, v1
	ds_bpermute_b32 v1, v113, v0
	s_waitcnt lgkmcnt(0)
	v_add_f32_e32 v0, v0, v1
	ds_bpermute_b32 v1, v114, v0
	s_waitcnt lgkmcnt(0)
	v_add_f32_e32 v0, v0, v1
	ds_bpermute_b32 v1, v115, v0
	s_waitcnt lgkmcnt(0)
	v_add_f32_e32 v0, v0, v1
	ds_bpermute_b32 v1, v116, v0
	s_waitcnt lgkmcnt(0)
	v_add_f32_e32 v0, v0, v1
	ds_bpermute_b32 v1, v117, v0
	s_waitcnt lgkmcnt(0)
	v_add_f32_e32 v0, v0, v1
	v_fmamk_f32 v0, v0, 0x3a000000, v207
	v_cmp_gt_f32_e32 vcc, s41, v0
	v_mul_f32_e32 v1, 0x4b800000, v0
	s_nop 0
	v_cndmask_b32_e32 v0, v0, v1, vcc
	v_rsq_f32_e32 v0, v0
	s_nop 0
	v_mul_f32_e32 v1, 0x45800000, v0
	v_cndmask_b32_e32 v24, v0, v1, vcc
	v_pk_mul_f32 v[0:1], v[60:61], v[24:25] op_sel_hi:[1,0]
	v_pk_mul_f32 v[2:3], v[54:55], v[24:25] op_sel_hi:[1,0]
	s_waitcnt vmcnt(0)
	v_pk_mul_f32 v[0:1], v[16:17], v[0:1]
	v_pk_mul_f32 v[2:3], v[18:19], v[2:3]
	v_cvt_pk_bf16_f32 v0, v0, v1
	v_cvt_pk_bf16_f32 v1, v2, v3
	v_pk_mul_f32 v[2:3], v[52:53], v[24:25] op_sel_hi:[1,0]
	v_pk_mul_f32 v[4:5], v[50:51], v[24:25] op_sel_hi:[1,0]
	v_pk_mul_f32 v[2:3], v[8:9], v[2:3]
	v_pk_mul_f32 v[4:5], v[10:11], v[4:5]
	v_cvt_pk_bf16_f32 v2, v2, v3
	v_cvt_pk_bf16_f32 v3, v4, v5
	global_store_dwordx4 v[48:49], v[0:3], off offset:2048
	s_nop 1
	v_mov_b64_e32 v[4:5], v[168:169]
	v_mov_b64_e32 v[6:7], v[170:171]
	v_mov_b64_e32 v[0:1], v[172:173]
	v_mov_b64_e32 v[2:3], v[174:175]
	v_pk_mul_f32 v[8:9], v[66:67], v[24:25] op_sel_hi:[1,0]
	v_lshl_add_u64 v[10:11], v[42:43], 0, v[148:149]
	v_lshl_add_u64 v[42:43], v[42:43], 0, s[12:13]
	v_pk_mul_f32 v[4:5], v[4:5], v[8:9]
	v_pk_mul_f32 v[8:9], v[76:77], v[24:25] op_sel_hi:[1,0]
	v_cvt_pk_bf16_f32 v4, v4, v5
	v_pk_mul_f32 v[6:7], v[6:7], v[8:9]
	v_pk_mul_f32 v[8:9], v[20:21], v[24:25] op_sel_hi:[1,0]
	v_cvt_pk_bf16_f32 v5, v6, v7
	v_pk_mul_f32 v[6:7], v[64:65], v[24:25] op_sel_hi:[1,0]
	s_nop 0
	v_pk_mul_f32 v[0:1], v[0:1], v[6:7]
	s_nop 0
	v_cvt_pk_bf16_f32 v6, v0, v1
	v_pk_mul_f32 v[0:1], v[58:59], v[24:25] op_sel_hi:[1,0]
	s_nop 0
	v_pk_mul_f32 v[0:1], v[2:3], v[0:1]
	s_nop 0
	v_cvt_pk_bf16_f32 v7, v0, v1
	global_store_dwordx4 v[48:49], v[4:7], off offset:2064
	s_nop 1
	v_mov_b64_e32 v[0:1], v[180:181]
	v_mov_b64_e32 v[2:3], v[182:183]
	v_mov_b64_e32 v[4:5], v[176:177]
	v_mov_b64_e32 v[6:7], v[178:179]
	v_pk_mul_f32 v[4:5], v[4:5], v[8:9]
	v_pk_mul_f32 v[8:9], v[30:31], v[24:25] op_sel_hi:[1,0]
	v_cvt_pk_bf16_f32 v4, v4, v5
	v_pk_mul_f32 v[6:7], v[6:7], v[8:9]
	v_pk_mul_f32 v[8:9], v[12:13], v[24:25] op_sel_hi:[1,0]
	v_cvt_pk_bf16_f32 v5, v6, v7
	v_pk_mul_f32 v[6:7], v[22:23], v[24:25] op_sel_hi:[1,0]
	s_nop 0
	v_pk_mul_f32 v[0:1], v[0:1], v[6:7]
	s_nop 0
	v_cvt_pk_bf16_f32 v6, v0, v1
	v_pk_mul_f32 v[0:1], v[78:79], v[24:25] op_sel_hi:[1,0]
	s_nop 0
	v_pk_mul_f32 v[0:1], v[2:3], v[0:1]
	s_nop 0
	v_cvt_pk_bf16_f32 v7, v0, v1
	global_store_dwordx4 v[48:49], v[4:7], off offset:2080
	s_nop 1
	v_mov_b64_e32 v[0:1], v[188:189]
	v_mov_b64_e32 v[2:3], v[190:191]
	v_mov_b64_e32 v[4:5], v[184:185]
	v_mov_b64_e32 v[6:7], v[186:187]
	v_pk_mul_f32 v[4:5], v[4:5], v[8:9]
	v_pk_mul_f32 v[8:9], v[88:89], v[24:25] op_sel_hi:[1,0]
	v_cvt_pk_bf16_f32 v4, v4, v5
	v_pk_mul_f32 v[6:7], v[6:7], v[8:9]
	s_nop 0
	v_cvt_pk_bf16_f32 v5, v6, v7
	v_pk_mul_f32 v[6:7], v[14:15], v[24:25] op_sel_hi:[1,0]
	v_lshl_add_u64 v[14:15], v[10:11], 0, s[18:19]
	v_pk_mul_f32 v[0:1], v[0:1], v[6:7]
	s_nop 0
	v_cvt_pk_bf16_f32 v6, v0, v1
	v_pk_mul_f32 v[0:1], v[28:29], v[24:25] op_sel_hi:[1,0]
	s_nop 0
	v_pk_mul_f32 v[0:1], v[2:3], v[0:1]
	v_add_co_u32_e32 v2, vcc, s3, v46
	v_cvt_pk_bf16_f32 v7, v0, v1
	global_store_dwordx4 v[48:49], v[4:7], off offset:2096
	v_lshl_add_u64 v[0:1], v[46:47], 0, s[4:5]
	v_addc_co_u32_e32 v3, vcc, 0, v47, vcc
	s_mov_b32 s3, 0x23d30000
	global_load_dwordx4 v[84:87], v[2:3], off
	global_load_dwordx4 v[22:25], v[0:1], off offset:48
	s_nop 0
	global_load_dwordx4 v[2:5], v[0:1], off offset:32
	global_load_dwordx4 v[6:9], v[0:1], off offset:16
	v_add_co_u32_e32 v0, vcc, s3, v10
	s_mov_b64 s[4:5], 0x8a02000
	s_nop 0
	v_addc_co_u32_e32 v1, vcc, 0, v11, vcc
	global_load_dwordx4 v[88:91], v[0:1], off
	global_load_dwordx4 v[118:121], v[14:15], off offset:48
	global_load_dwordx4 v[10:13], v[14:15], off offset:32
	s_nop 0
	global_load_dwordx4 v[14:17], v[14:15], off offset:16
	s_mov_b32 s3, 0x8a03000
	s_waitcnt vmcnt(7)
	v_lshlrev_b32_e32 v70, 16, v87
	s_waitcnt vmcnt(6)
	v_lshlrev_b32_e32 v78, 16, v22
	s_waitcnt vmcnt(5)
	v_lshlrev_b32_e32 v56, 16, v2
	s_waitcnt vmcnt(4)
	v_lshlrev_b32_e32 v0, 16, v6
	v_and_b32_e32 v1, 0xffff0000, v6
	v_lshlrev_b32_e32 v94, 16, v7
	v_and_b32_e32 v95, 0xffff0000, v7
	v_and_b32_e32 v57, 0xffff0000, v2
	v_lshlrev_b32_e32 v58, 16, v3
	s_waitcnt vmcnt(0)
; __device__ __forceinline__ float bflo(unsigned w) { return __uint_as_float(w << 16); }
; __device__ __forceinline__ float bfhi(unsigned w) { return __uint_as_float(w & 0xFFFF0000u); }
; __device__ __forceinline__ float siluf(float v) { return v * __builtin_amdgcn_rcpf(1.f + __expf(-v)); }
; __device__ __forceinline__ float sigmf(float v) { return __builtin_amdgcn_rcpf(1.f + __expf(-v)); }
; __device__ void phase_post(const Params& p, int l) {
;     ...
;             float hv[32]; float s = 0.f;
; #pragma unroll
;             for (int q = 0; q < 4; ++q) { const u32x4 a = *(const u32x4*)(pr + c0 + q * 8), ab = *(const u32x4*)(p.HB + (size_t)row * 2048 + c0 + q * 8);
; #pragma unroll
;                 for (int e = 0; e < 4; ++e) { const float h0 = bflo(a[e]) + bflo(ab[e]), h1 = bfhi(a[e]) + bfhi(ab[e]); hv[q * 8 + 2 * e] = h0; hv[q * 8 + 2 * e + 1] = h1; s += h0 + h1; } }
;     ...
;             for (int q = 0; q < 4; ++q) { const u32x4 ov = *(const u32x4*)(pr + 4096 + c0 + q * 8), zv = *(const u32x4*)(pr + 6144 + c0 + q * 8);
;                 const f32x4 wa = *(const f32x4*)(mw + q * 8), wb = *(const f32x4*)(mw + q * 8 + 4);
;                 float r[8];
; #pragma unroll
;                 for (int e = 0; e < 4; ++e) {
;                     const float m0 = (e < 2 ? wa[2 * e] : wb[2 * e - 4]), m1 = (e < 2 ? wa[2 * e + 1] : wb[2 * e - 3]);
;                     r[2 * e] = sigmf(bflo(ov[e])) * ((hv[q * 8 + 2 * e] - mean) * rstd * m0) * siluf(bflo(zv[e]));
;                     r[2 * e + 1] = sigmf(bfhi(ov[e])) * ((hv[q * 8 + 2 * e + 1] - mean) * rstd * m1) * siluf(bfhi(zv[e])); }
	v_lshlrev_b32_e32 v18, 16, v14
	v_and_b32_e32 v19, 0xffff0000, v14
	v_pk_add_f32 v[26:27], v[0:1], v[18:19]
	v_lshlrev_b32_e32 v0, 16, v9
	v_and_b32_e32 v1, 0xffff0000, v9
	v_lshlrev_b32_e32 v6, 16, v17
	v_and_b32_e32 v7, 0xffff0000, v17
	v_pk_add_f32 v[30:31], v[0:1], v[6:7]
	v_lshlrev_b32_e32 v0, 16, v4
	v_pk_add_f32 v[104:105], v[30:31], v[30:31] op_sel_hi:[0,1]
	v_and_b32_e32 v104, 0xffff0000, v3
	v_and_b32_e32 v1, 0xffff0000, v4
	v_lshlrev_b32_e32 v2, 16, v12
	v_and_b32_e32 v3, 0xffff0000, v12
	v_pk_add_f32 v[48:49], v[0:1], v[2:3]
	v_lshlrev_b32_e32 v0, 16, v23
	v_and_b32_e32 v1, 0xffff0000, v23
	v_lshlrev_b32_e32 v2, 16, v119
	v_and_b32_e32 v3, 0xffff0000, v119
	v_pk_add_f32 v[92:93], v[26:27], v[26:27] op_sel_hi:[0,1]
	v_pk_add_f32 v[28:29], v[0:1], v[2:3]
	v_lshl_add_u64 v[0:1], v[46:47], 0, s[4:5]
	s_mov_b64 s[4:5], 0x8a03000
	v_add_co_u32_e32 v2, vcc, s3, v46
	v_lshlrev_b32_e32 v96, 16, v8
	v_and_b32_e32 v92, 0xffff0000, v8
	v_pk_add_f32 v[66:67], v[48:49], v[48:49] op_sel_hi:[0,1]
	v_lshl_add_u64 v[8:9], v[46:47], 0, s[4:5]
	v_addc_co_u32_e32 v3, vcc, 0, v47, vcc
	v_lshlrev_b32_e32 v98, 16, v15
	v_and_b32_e32 v99, 0xffff0000, v15
	v_lshlrev_b32_e32 v100, 16, v16
	v_and_b32_e32 v102, 0xffff0000, v16
	v_lshlrev_b32_e32 v60, 16, v10
	v_and_b32_e32 v61, 0xffff0000, v10
	v_lshlrev_b32_e32 v62, 16, v11
	v_and_b32_e32 v106, 0xffff0000, v11
	v_lshlrev_b32_e32 v76, 16, v5
	v_lshlrev_b32_e32 v80, 16, v13
	v_and_b32_e32 v81, 0xffff0000, v13
	v_and_b32_e32 v77, 0xffff0000, v5
	v_and_b32_e32 v66, 0xffff0000, v22
	global_load_dwordx4 v[52:55], v[2:3], off offset:-4096
	global_load_dwordx4 v[4:7], v[0:1], off offset:48
	global_load_dwordx4 v[20:23], v[0:1], off offset:32
	global_load_dwordx4 v[122:125], v[0:1], off offset:16
	global_load_dwordx4 v[126:129], v[2:3], off
	s_nop 0
	global_load_dwordx4 v[0:3], v[8:9], off offset:48
	global_load_dwordx4 v[16:19], v[8:9], off offset:32
	global_load_dwordx4 v[130:133], v[8:9], off offset:16
	s_nop 0
	v_pk_add_f32 v[64:65], v[28:29], v[28:29] op_sel_hi:[0,1]
	v_lshlrev_b32_e32 v82, 16, v118
	v_mov_b64_e32 v[8:9], v[196:197]
	v_mov_b64_e32 v[10:11], v[198:199]
	v_mov_b64_e32 v[12:13], v[192:193]
	v_mov_b64_e32 v[14:15], v[194:195]
	v_and_b32_e32 v72, 0xffff0000, v118
	v_lshlrev_b32_e32 v118, 16, v25
	v_and_b32_e32 v64, 0xffff0000, v25
	v_and_b32_e32 v71, 0xffff0000, v87
	v_lshlrev_b32_e32 v74, 16, v91
	v_and_b32_e32 v75, 0xffff0000, v91
	v_pk_add_f32 v[108:109], v[70:71], v[74:75]
	v_lshlrev_b32_e32 v70, 16, v86
	v_and_b32_e32 v71, 0xffff0000, v86
	v_lshlrev_b32_e32 v74, 16, v90
	v_and_b32_e32 v75, 0xffff0000, v90
	v_pk_add_f32 v[110:111], v[70:71], v[74:75]
	v_mov_b32_e32 v70, v108
	v_mov_b32_e32 v71, v110
	v_mov_b32_e32 v74, v109
	v_mov_b32_e32 v75, v111
	v_pk_add_f32 v[86:87], v[70:71], v[74:75]
	v_lshlrev_b32_e32 v90, 16, v89
	v_and_b32_e32 v91, 0xffff0000, v89
	v_lshlrev_b32_e32 v134, 16, v121
	v_and_b32_e32 v68, 0xffff0000, v121
	v_pk_add_f32 v[76:77], v[76:77], v[80:81]
	v_pk_add_f32 v[56:57], v[56:57], v[60:61]
	v_mov_b32_e32 v79, v76
	v_mov_b32_e32 v83, v77
	v_pk_add_f32 v[78:79], v[78:79], v[82:83]
	v_mov_b32_e32 v59, v56
	v_mov_b32_e32 v63, v57
	v_pk_add_f32 v[58:59], v[58:59], v[62:63]
	s_waitcnt vmcnt(7)
	v_lshlrev_b32_e32 v25, 16, v52
	v_mul_f32_e32 v25, 0xbfb8aa3b, v25
	v_exp_f32_e32 v25, v25
	s_waitcnt vmcnt(3)
	v_lshlrev_b32_e32 v70, 16, v128
	v_and_b32_e32 v71, 0xffff0000, v128
	v_add_f32_e32 v25, 1.0, v25
	v_rcp_f32_e32 v46, v25
	v_and_b32_e32 v25, 0xffff0000, v52
	v_mul_f32_e32 v25, 0xbfb8aa3b, v25
	v_exp_f32_e32 v25, v25
	s_waitcnt vmcnt(1)
	v_lshlrev_b32_e32 v80, 16, v18
	v_and_b32_e32 v81, 0xffff0000, v18
	v_mul_f32_e32 v18, 0xbfb8aa3b, v80
	v_add_f32_e32 v25, 1.0, v25
	v_rcp_f32_e32 v47, v25
	v_lshlrev_b32_e32 v25, 16, v53
	v_mul_f32_e32 v25, 0xbfb8aa3b, v25
	v_exp_f32_e32 v25, v25
	v_exp_f32_e32 v18, v18
	v_lshlrev_b32_e32 v62, 16, v16
	v_and_b32_e32 v63, 0xffff0000, v16
	v_add_f32_e32 v25, 1.0, v25
	v_rcp_f32_e32 v50, v25
	v_and_b32_e32 v25, 0xffff0000, v53
	v_mul_f32_e32 v25, 0xbfb8aa3b, v25
	v_exp_f32_e32 v25, v25
	v_add_f32_e32 v18, 1.0, v18
	v_rcp_f32_e32 v82, v18
	v_mul_f32_e32 v18, 0xbfb8aa3b, v81
	v_add_f32_e32 v25, 1.0, v25
	v_rcp_f32_e32 v51, v25
	v_lshlrev_b32_e32 v25, 16, v54
	v_mul_f32_e32 v25, 0xbfb8aa3b, v25
	v_exp_f32_e32 v25, v25
	v_exp_f32_e32 v18, v18
	v_mul_f32_e32 v16, 0xbfb8aa3b, v62
	v_exp_f32_e32 v16, v16
	v_add_f32_e32 v25, 1.0, v25
	v_rcp_f32_e32 v52, v25
	v_and_b32_e32 v25, 0xffff0000, v54
	v_mul_f32_e32 v25, 0xbfb8aa3b, v25
	v_exp_f32_e32 v25, v25
	v_add_f32_e32 v18, 1.0, v18
	v_rcp_f32_e32 v83, v18
	v_add_f32_e32 v16, 1.0, v16
	v_add_f32_e32 v25, 1.0, v25
	v_rcp_f32_e32 v53, v25
	v_lshlrev_b32_e32 v25, 16, v55
	v_mul_f32_e32 v25, 0xbfb8aa3b, v25
	v_exp_f32_e32 v25, v25
	v_pk_mul_f32 v[80:81], v[82:83], v[80:81]
	v_lshlrev_b32_e32 v82, 16, v17
	v_and_b32_e32 v83, 0xffff0000, v17
	v_add_f32_e32 v25, 1.0, v25
	v_rcp_f32_e32 v54, v25
	v_and_b32_e32 v25, 0xffff0000, v55
	v_mul_f32_e32 v25, 0xbfb8aa3b, v25
	v_exp_f32_e32 v25, v25
	v_mul_f32_e32 v17, 0xbfb8aa3b, v82
	v_exp_f32_e32 v17, v17
	v_rcp_f32_e32 v16, v16
	v_add_f32_e32 v25, 1.0, v25
	v_rcp_f32_e32 v55, v25
	v_mul_f32_e32 v25, 0xbfb8aa3b, v70
	v_exp_f32_e32 v25, v25
	v_add_f32_e32 v17, 1.0, v17
	v_lshlrev_b32_e32 v146, 16, v19
	v_and_b32_e32 v147, 0xffff0000, v19
	v_add_f32_e32 v25, 1.0, v25
	v_rcp_f32_e32 v74, v25
	v_mul_f32_e32 v25, 0xbfb8aa3b, v71
	v_exp_f32_e32 v25, v25
	s_nop 0
	v_add_f32_e32 v25, 1.0, v25
	v_rcp_f32_e32 v75, v25
	s_nop 0
	v_pk_mul_f32 v[70:71], v[74:75], v[70:71]
	v_lshlrev_b32_e32 v74, 16, v85
	v_and_b32_e32 v75, 0xffff0000, v85
	v_pk_add_f32 v[136:137], v[74:75], v[90:91]
; __device__ __forceinline__ float bflo(unsigned w) { return __uint_as_float(w << 16); }
; __device__ __forceinline__ float bfhi(unsigned w) { return __uint_as_float(w & 0xFFFF0000u); }
; __device__ __forceinline__ float siluf(float v) { return v * __builtin_amdgcn_rcpf(1.f + __expf(-v)); }
; __device__ __forceinline__ float sigmf(float v) { return __builtin_amdgcn_rcpf(1.f + __expf(-v)); }
; __device__ void phase_post(const Params& p, int l) {
;     ...
;             for (int q = 0; q < 4; ++q) { const u32x4 a = *(const u32x4*)(pr + c0 + q * 8), ab = *(const u32x4*)(p.HB + (size_t)row * 2048 + c0 + q * 8);
; #pragma unroll
;                 for (int e = 0; e < 4; ++e) { const float h0 = bflo(a[e]) + bflo(ab[e]), h1 = bfhi(a[e]) + bfhi(ab[e]); hv[q * 8 + 2 * e] = h0; hv[q * 8 + 2 * e + 1] = h1; s += h0 + h1; } }
;             s += __shfl_xor(s, 1, 64); s += __shfl_xor(s, 2, 64); s += __shfl_xor(s, 4, 64);
;     ...
;                 for (int e = 0; e < 4; ++e) {
;                     const float m0 = (e < 2 ? wa[2 * e] : wb[2 * e - 4]), m1 = (e < 2 ? wa[2 * e + 1] : wb[2 * e - 3]);
;                     r[2 * e] = sigmf(bflo(ov[e])) * ((hv[q * 8 + 2 * e] - mean) * rstd * m0) * siluf(bflo(zv[e]));
;                     r[2 * e + 1] = sigmf(bfhi(ov[e])) * ((hv[q * 8 + 2 * e + 1] - mean) * rstd * m1) * siluf(bfhi(zv[e])); }
	v_lshlrev_b32_e32 v74, 16, v127
	v_mul_f32_e32 v25, 0xbfb8aa3b, v74
	v_exp_f32_e32 v25, v25
	v_and_b32_e32 v75, 0xffff0000, v127
	v_and_b32_e32 v85, 0xffff0000, v88
	v_add_f32_e32 v25, 1.0, v25
	v_rcp_f32_e32 v90, v25
	v_mul_f32_e32 v25, 0xbfb8aa3b, v75
	v_exp_f32_e32 v25, v25
	s_nop 0
	v_add_f32_e32 v25, 1.0, v25
	v_rcp_f32_e32 v91, v25
	s_nop 0
	v_pk_mul_f32 v[74:75], v[90:91], v[74:75]
	v_lshlrev_b32_e32 v90, 16, v84
	v_and_b32_e32 v91, 0xffff0000, v84
	v_lshlrev_b32_e32 v84, 16, v88
	v_pk_add_f32 v[138:139], v[90:91], v[84:85]
	v_mov_b32_e32 v84, v136
	v_mov_b32_e32 v85, v138
	v_mov_b32_e32 v88, v137
	v_mov_b32_e32 v89, v139
	v_pk_add_f32 v[88:89], v[84:85], v[88:89]
	v_lshlrev_b32_e32 v84, 16, v126
	v_mul_f32_e32 v33, 0xbfb8aa3b, v84
	v_exp_f32_e32 v33, v33
	v_and_b32_e32 v85, 0xffff0000, v126
	v_add_f32_e32 v25, 0, v89
	v_add_f32_e32 v25, v88, v25
	v_add_f32_e32 v33, 1.0, v33
	v_rcp_f32_e32 v90, v33
	v_mul_f32_e32 v33, 0xbfb8aa3b, v85
	v_exp_f32_e32 v33, v33
	v_add_f32_e32 v25, v87, v25
	v_add_f32_e32 v103, v86, v25
	v_and_b32_e32 v86, 0xffff0000, v24
	v_lshlrev_b32_e32 v87, 16, v24
	v_and_b32_e32 v24, 0xffff0000, v120
	v_lshlrev_b32_e32 v25, 16, v120
	v_add_f32_e32 v33, 1.0, v33
	v_pk_add_f32 v[120:121], v[86:87], v[24:25]
	v_lshlrev_b32_e32 v24, 16, v129
	v_rcp_f32_e32 v91, v33
	v_mul_f32_e32 v33, 0xbfb8aa3b, v24
	v_exp_f32_e32 v33, v33
	v_and_b32_e32 v25, 0xffff0000, v129
	v_pk_mul_f32 v[84:85], v[90:91], v[84:85]
	v_pk_add_f32 v[126:127], v[92:93], v[102:103]
	v_add_f32_e32 v33, 1.0, v33
	v_rcp_f32_e32 v86, v33
	v_mul_f32_e32 v33, 0xbfb8aa3b, v25
	v_exp_f32_e32 v33, v33
	s_waitcnt vmcnt(0)
	v_lshlrev_b32_e32 v102, 16, v132
	v_and_b32_e32 v103, 0xffff0000, v132
	v_mov_b32_e32 v119, v121
	v_add_f32_e32 v33, 1.0, v33
	v_rcp_f32_e32 v87, v33
	v_lshlrev_b32_e32 v33, 16, v123
	v_mul_f32_e32 v33, 0xbfb8aa3b, v33
	v_exp_f32_e32 v33, v33
	v_pk_mul_f32 v[86:87], v[86:87], v[24:25]
	v_lshlrev_b32_e32 v24, 16, v122
	v_and_b32_e32 v25, 0xffff0000, v122
	v_add_f32_e32 v33, 1.0, v33
	v_rcp_f32_e32 v88, v33
	v_and_b32_e32 v33, 0xffff0000, v123
	v_mul_f32_e32 v33, 0xbfb8aa3b, v33
	v_exp_f32_e32 v33, v33
	v_mov_b32_e32 v135, v120
	v_pk_add_f32 v[118:119], v[118:119], v[134:135]
	v_mul_f32_e32 v24, 0xbfb8aa3b, v24
	v_add_f32_e32 v33, 1.0, v33
	v_rcp_f32_e32 v89, v33
	v_lshlrev_b32_e32 v33, 16, v124
	v_mul_f32_e32 v33, 0xbfb8aa3b, v33
	v_exp_f32_e32 v33, v33
	v_mul_f32_e32 v25, 0xbfb8aa3b, v25
	v_exp_f32_e32 v24, v24
	v_exp_f32_e32 v25, v25
	v_add_f32_e32 v33, 1.0, v33
	v_rcp_f32_e32 v90, v33
	v_and_b32_e32 v33, 0xffff0000, v124
	v_mul_f32_e32 v33, 0xbfb8aa3b, v33
	v_exp_f32_e32 v33, v33
	v_add_f32_e32 v24, 1.0, v24
	v_add_f32_e32 v25, 1.0, v25
	v_rcp_f32_e32 v24, v24
	v_add_f32_e32 v33, 1.0, v33
	v_rcp_f32_e32 v91, v33
	v_lshlrev_b32_e32 v33, 16, v125
	v_mul_f32_e32 v33, 0xbfb8aa3b, v33
	v_exp_f32_e32 v33, v33
	v_rcp_f32_e32 v25, v25
	v_add_f32_e32 v33, 1.0, v33
	v_rcp_f32_e32 v92, v33
	v_and_b32_e32 v33, 0xffff0000, v125
	v_mul_f32_e32 v33, 0xbfb8aa3b, v33
	v_exp_f32_e32 v33, v33
	s_nop 0
	v_add_f32_e32 v33, 1.0, v33
	v_rcp_f32_e32 v93, v33
	v_mul_f32_e32 v33, 0xbfb8aa3b, v102
	v_exp_f32_e32 v33, v33
	s_nop 0
	v_add_f32_e32 v33, 1.0, v33
	v_rcp_f32_e32 v122, v33
	v_mul_f32_e32 v33, 0xbfb8aa3b, v103
	v_exp_f32_e32 v33, v33
	s_nop 0
	v_add_f32_e32 v33, 1.0, v33
	v_rcp_f32_e32 v123, v33
	s_nop 0
	v_pk_mul_f32 v[102:103], v[122:123], v[102:103]
	v_pk_add_f32 v[122:123], v[94:95], v[98:99]
	s_nop 0
	v_mov_b32_e32 v97, v122
	v_mov_b32_e32 v101, v123
	v_pk_add_f32 v[124:125], v[96:97], v[100:101]
	s_nop 0
	v_pk_add_f32 v[94:95], v[124:125], v[126:127]
	v_mov_b32_e32 v125, v126
	v_pk_add_f32 v[94:95], v[94:95], v[94:95] op_sel_hi:[0,1]
	v_lshlrev_b32_e32 v94, 16, v131
	v_mul_f32_e32 v33, 0xbfb8aa3b, v94
	v_exp_f32_e32 v33, v33
	v_mov_b32_e32 v107, v95
	v_and_b32_e32 v95, 0xffff0000, v131
	v_rcp_f32_e32 v126, v17
	v_add_f32_e32 v33, 1.0, v33
	v_rcp_f32_e32 v96, v33
	v_mul_f32_e32 v33, 0xbfb8aa3b, v95
	v_exp_f32_e32 v33, v33
	v_mul_f32_e32 v17, 0xbfb8aa3b, v83
	v_exp_f32_e32 v17, v17
	v_pk_add_f32 v[104:105], v[104:105], v[106:107]
	v_add_f32_e32 v33, 1.0, v33
	v_rcp_f32_e32 v97, v33
	v_add_f32_e32 v17, 1.0, v17
	v_rcp_f32_e32 v127, v17
	v_mul_f32_e32 v17, 0xbfb8aa3b, v63
	v_pk_mul_f32 v[94:95], v[96:97], v[94:95]
	v_lshlrev_b32_e32 v96, 16, v130
	v_mul_f32_e32 v33, 0xbfb8aa3b, v96
	v_exp_f32_e32 v33, v33
	v_and_b32_e32 v97, 0xffff0000, v130
	v_exp_f32_e32 v17, v17
	v_pk_add_f32 v[60:61], v[58:59], v[104:105]
	v_add_f32_e32 v33, 1.0, v33
	v_rcp_f32_e32 v98, v33
	v_mul_f32_e32 v33, 0xbfb8aa3b, v97
	v_exp_f32_e32 v33, v33
	v_add_f32_e32 v17, 1.0, v17
	v_rcp_f32_e32 v17, v17
	v_pk_add_f32 v[60:61], v[60:61], v[60:61] op_sel_hi:[0,1]
	v_add_f32_e32 v33, 1.0, v33
	v_rcp_f32_e32 v99, v33
	v_mov_b32_e32 v73, v61
	v_pk_add_f32 v[60:61], v[66:67], v[72:73]
	v_pk_mul_f32 v[16:17], v[16:17], v[62:63]
	v_pk_mul_f32 v[100:101], v[98:99], v[96:97]
	v_lshlrev_b32_e32 v96, 16, v133
	v_mul_f32_e32 v33, 0xbfb8aa3b, v96
	v_exp_f32_e32 v33, v33
	v_and_b32_e32 v97, 0xffff0000, v133
	v_pk_add_f32 v[62:63], v[78:79], v[60:61]
	v_mov_b32_e32 v59, v104
	v_add_f32_e32 v33, 1.0, v33
	v_rcp_f32_e32 v98, v33
	v_mul_f32_e32 v33, 0xbfb8aa3b, v97
	v_exp_f32_e32 v33, v33
	v_pk_add_f32 v[62:63], v[62:63], v[62:63] op_sel_hi:[0,1]
	v_mov_b32_e32 v69, v63
	v_pk_add_f32 v[62:63], v[64:65], v[68:69]
	v_add_f32_e32 v33, 1.0, v33
	v_rcp_f32_e32 v99, v33
	v_lshlrev_b32_e32 v33, 16, v20
	v_mul_f32_e32 v33, 0xbfb8aa3b, v33
	v_exp_f32_e32 v33, v33
	v_pk_mul_f32 v[98:99], v[98:99], v[96:97]
	v_pk_add_f32 v[64:65], v[118:119], v[62:63]
	v_mov_b32_e32 v63, v118
	v_add_f32_e32 v33, 1.0, v33
	v_rcp_f32_e32 v96, v33
	v_lshlrev_b32_e32 v33, 16, v22
	v_mul_f32_e32 v33, 0xbfb8aa3b, v33
	v_exp_f32_e32 v33, v33
	v_add_f32_e32 v18, v64, v65
	v_mov_b32_e32 v79, v60
	v_pk_mul_f32 v[82:83], v[126:127], v[82:83]
	v_add_f32_e32 v33, 1.0, v33
	v_rcp_f32_e32 v106, v33
	ds_bpermute_b32 v33, v117, v18
	v_and_b32_e32 v20, 0xffff0000, v20
	v_and_b32_e32 v22, 0xffff0000, v22
	v_mul_f32_e32 v20, 0xbfb8aa3b, v20
	v_mul_f32_e32 v22, 0xbfb8aa3b, v22
	s_waitcnt lgkmcnt(0)
; __device__ void phase_post(const Params& p, int l) {
;     ...
;             s += __shfl_xor(s, 1, 64); s += __shfl_xor(s, 2, 64); s += __shfl_xor(s, 4, 64);
;             const float mean = s * (1.f / 256.f);
;             float q2 = 0.f;
; #pragma unroll
;             for (int e = 0; e < 32; ++e) { const float d = hv[e] - mean; q2 += d * d; }
;             q2 += __shfl_xor(q2, 1, 64); q2 += __shfl_xor(q2, 2, 64); q2 += __shfl_xor(q2, 4, 64);
;             const float rstd = rsqrtf(q2 * (1.f / 256.f) + LN_EPS);
	v_add_f32_e32 v18, v18, v33
	ds_bpermute_b32 v33, v116, v18
	v_exp_f32_e32 v20, v20
	v_exp_f32_e32 v22, v22
	s_waitcnt lgkmcnt(0)
	v_add_f32_e32 v18, v18, v33
	ds_bpermute_b32 v33, v115, v18
	v_add_f32_e32 v20, 1.0, v20
	v_add_f32_e32 v22, 1.0, v22
	v_rcp_f32_e32 v97, v20
	v_lshlrev_b32_e32 v20, 16, v21
	s_waitcnt lgkmcnt(0)
	v_add_f32_e32 v18, v18, v33
	v_mul_f32_e32 v18, 0x3b800000, v18
	v_pk_add_f32 v[64:65], v[138:139], v[18:19] op_sel_hi:[1,0] neg_lo:[0,1] neg_hi:[0,1]
	v_pk_add_f32 v[68:69], v[136:137], v[18:19] op_sel_hi:[1,0] neg_lo:[0,1] neg_hi:[0,1]
	v_pk_add_f32 v[110:111], v[110:111], v[18:19] op_sel_hi:[1,0] neg_lo:[0,1] neg_hi:[0,1]
	v_pk_add_f32 v[108:109], v[108:109], v[18:19] op_sel_hi:[1,0] neg_lo:[0,1] neg_hi:[0,1]
	v_pk_add_f32 v[122:123], v[122:123], v[18:19] op_sel_hi:[1,0] neg_lo:[0,1] neg_hi:[0,1]
	v_pk_add_f32 v[56:57], v[56:57], v[18:19] op_sel_hi:[1,0] neg_lo:[0,1] neg_hi:[0,1]
	v_pk_add_f32 v[76:77], v[76:77], v[18:19] op_sel_hi:[1,0] neg_lo:[0,1] neg_hi:[0,1]
	v_pk_add_f32 v[120:121], v[120:121], v[18:19] op_sel_hi:[1,0] neg_lo:[0,1] neg_hi:[0,1]
	v_pk_add_f32 v[62:63], v[62:63], v[18:19] op_sel_hi:[1,0] neg_lo:[0,1] neg_hi:[0,1]
	v_pk_add_f32 v[30:31], v[30:31], v[18:19] op_sel_hi:[1,0] neg_lo:[0,1] neg_hi:[0,1]
	v_pk_add_f32 v[124:125], v[124:125], v[18:19] op_sel_hi:[1,0] neg_lo:[0,1] neg_hi:[0,1]
	v_pk_add_f32 v[26:27], v[26:27], v[18:19] op_sel_hi:[1,0] neg_lo:[0,1] neg_hi:[0,1]
	v_pk_add_f32 v[48:49], v[48:49], v[18:19] op_sel_hi:[1,0] neg_lo:[0,1] neg_hi:[0,1]
	v_pk_add_f32 v[58:59], v[58:59], v[18:19] op_sel_hi:[1,0] neg_lo:[0,1] neg_hi:[0,1]
	v_mul_f32_e32 v19, 0xbfb8aa3b, v146
	v_exp_f32_e32 v19, v19
	v_pk_mul_f32 v[66:67], v[64:65], v[64:65]
	v_pk_mul_f32 v[72:73], v[68:69], v[68:69]
	v_pk_mul_f32 v[126:127], v[110:111], v[110:111]
	v_add_f32_e32 v19, 1.0, v19
	v_rcp_f32_e32 v150, v19
	v_mul_f32_e32 v19, 0xbfb8aa3b, v147
	v_exp_f32_e32 v19, v19
	v_pk_mul_f32 v[128:129], v[108:109], v[108:109]
	v_pk_mul_f32 v[142:143], v[26:27], v[26:27]
	v_pk_mul_f32 v[130:131], v[122:123], v[122:123]
	v_add_f32_e32 v19, 1.0, v19
	v_rcp_f32_e32 v151, v19
	v_lshlrev_b32_e32 v19, 16, v4
	v_mul_f32_e32 v19, 0xbfb8aa3b, v19
	v_exp_f32_e32 v19, v19
	v_pk_mul_f32 v[146:147], v[150:151], v[146:147]
	v_pk_mul_f32 v[140:141], v[124:125], v[124:125]
	v_pk_mul_f32 v[138:139], v[30:31], v[30:31]
	v_add_f32_e32 v19, 1.0, v19
	v_rcp_f32_e32 v150, v19
	v_pk_add_f32 v[28:29], v[28:29], v[18:19] op_sel_hi:[1,0] neg_lo:[0,1] neg_hi:[0,1]
	v_pk_add_f32 v[18:19], v[78:79], v[18:19] op_sel_hi:[1,0] neg_lo:[0,1] neg_hi:[0,1]
	v_lshlrev_b32_e32 v78, 16, v0
	v_and_b32_e32 v79, 0xffff0000, v0
	v_mul_f32_e32 v0, 0xbfb8aa3b, v78
	v_exp_f32_e32 v0, v0
	v_pk_mul_f32 v[132:133], v[56:57], v[56:57]
	v_pk_mul_f32 v[104:105], v[58:59], v[58:59]
	v_pk_mul_f32 v[144:145], v[48:49], v[48:49]
	v_add_f32_e32 v0, 1.0, v0
	v_rcp_f32_e32 v158, v0
	v_mul_f32_e32 v0, 0xbfb8aa3b, v79
	v_exp_f32_e32 v0, v0
	v_pk_mul_f32 v[134:135], v[76:77], v[76:77]
	v_pk_mul_f32 v[60:61], v[18:19], v[18:19]
	v_pk_mul_f32 v[152:153], v[28:29], v[28:29]
	v_add_f32_e32 v0, 1.0, v0
	v_rcp_f32_e32 v159, v0
	v_add_f32_e32 v0, v66, v67
	v_add_f32_e32 v0, v72, v0
	v_add_f32_e32 v0, v73, v0
	v_add_f32_e32 v0, v126, v0
	v_add_f32_e32 v0, v127, v0
	v_add_f32_e32 v0, v128, v0
	v_add_f32_e32 v0, v129, v0
	v_add_f32_e32 v0, v142, v0
	v_add_f32_e32 v0, v143, v0
	v_add_f32_e32 v0, v130, v0
	v_add_f32_e32 v0, v131, v0
	v_add_f32_e32 v0, v140, v0
	v_add_f32_e32 v0, v141, v0
	v_add_f32_e32 v0, v138, v0
	v_add_f32_e32 v0, v139, v0
	v_add_f32_e32 v0, v132, v0
	v_add_f32_e32 v0, v133, v0
	v_add_f32_e32 v0, v104, v0
	v_add_f32_e32 v0, v105, v0
	v_add_f32_e32 v0, v144, v0
	v_add_f32_e32 v0, v145, v0
	v_add_f32_e32 v0, v134, v0
	v_add_f32_e32 v0, v135, v0
	v_add_f32_e32 v0, v60, v0
	v_add_f32_e32 v0, v61, v0
	v_add_f32_e32 v0, v152, v0
	v_pk_mul_f32 v[136:137], v[120:121], v[120:121]
	v_add_f32_e32 v0, v153, v0
	v_add_f32_e32 v0, v137, v0
	v_pk_mul_f32 v[118:119], v[62:63], v[62:63]
	v_add_f32_e32 v0, v136, v0
	v_add_f32_e32 v0, v119, v0
	v_add_f32_e32 v0, v118, v0
	ds_bpermute_b32 v33, v117, v0
	v_and_b32_e32 v21, 0xffff0000, v21
	v_rcp_f32_e32 v107, v22
	v_lshlrev_b32_e32 v22, 16, v23
	v_and_b32_e32 v23, 0xffff0000, v23
	s_waitcnt lgkmcnt(0)
	v_add_f32_e32 v0, v0, v33
	ds_bpermute_b32 v33, v116, v0
	v_mul_f32_e32 v20, 0xbfb8aa3b, v20
	v_mul_f32_e32 v21, 0xbfb8aa3b, v21
	v_mul_f32_e32 v22, 0xbfb8aa3b, v22
	v_mul_f32_e32 v23, 0xbfb8aa3b, v23
	s_waitcnt lgkmcnt(0)
	v_add_f32_e32 v0, v0, v33
	ds_bpermute_b32 v33, v115, v0
	v_exp_f32_e32 v20, v20
	v_exp_f32_e32 v21, v21
	v_exp_f32_e32 v22, v22
	v_exp_f32_e32 v23, v23
	s_waitcnt lgkmcnt(0)
	v_add_f32_e32 v0, v0, v33
	v_fmamk_f32 v0, v0, 0x3b800000, v207
	v_cmp_gt_f32_e32 vcc, s41, v0
	v_mul_f32_e32 v33, 0x4b800000, v0
	v_add_f32_e32 v20, 1.0, v20
	v_cndmask_b32_e32 v0, v0, v33, vcc
	v_rsq_f32_e32 v0, v0
	v_add_f32_e32 v21, 1.0, v21
	v_add_f32_e32 v22, 1.0, v22
	v_add_f32_e32 v23, 1.0, v23
	v_mul_f32_e32 v33, 0x45800000, v0
	v_cndmask_b32_e32 v0, v0, v33, vcc
	v_pk_mul_f32 v[60:61], v[64:65], v[0:1] op_sel_hi:[1,0]
	v_pk_mul_f32 v[26:27], v[26:27], v[0:1] op_sel_hi:[1,0]
	s_waitcnt vmcnt(0)
; __device__ __forceinline__ float bflo(unsigned w) { return __uint_as_float(w << 16); }
; __device__ __forceinline__ float bfhi(unsigned w) { return __uint_as_float(w & 0xFFFF0000u); }
; __device__ __forceinline__ unsigned pk2(float lo, float hi) { const f32x2_t v = {lo, hi}; return __builtin_bit_cast(unsigned, __builtin_convertvector(v, bf16x2_t)); }
; __device__ __forceinline__ float siluf(float v) { return v * __builtin_amdgcn_rcpf(1.f + __expf(-v)); }
; __device__ __forceinline__ float sigmf(float v) { return __builtin_amdgcn_rcpf(1.f + __expf(-v)); }
; __device__ void phase_post(const Params& p, int l) {
;     ...
;             const float* mw = p.mh_w + (size_t)l * 2048 + c0;
; #pragma unroll
;             for (int q = 0; q < 4; ++q) { const u32x4 ov = *(const u32x4*)(pr + 4096 + c0 + q * 8), zv = *(const u32x4*)(pr + 6144 + c0 + q * 8);
;                 const f32x4 wa = *(const f32x4*)(mw + q * 8), wb = *(const f32x4*)(mw + q * 8 + 4);
;                 float r[8];
; #pragma unroll
;                 for (int e = 0; e < 4; ++e) {
;                     const float m0 = (e < 2 ? wa[2 * e] : wb[2 * e - 4]), m1 = (e < 2 ? wa[2 * e + 1] : wb[2 * e - 3]);
;                     r[2 * e] = sigmf(bflo(ov[e])) * ((hv[q * 8 + 2 * e] - mean) * rstd * m0) * siluf(bflo(zv[e]));
;                     r[2 * e + 1] = sigmf(bfhi(ov[e])) * ((hv[q * 8 + 2 * e + 1] - mean) * rstd * m1) * siluf(bfhi(zv[e])); }
;                 u32x4 o; o.x = pk2(r[0], r[1]); o.y = pk2(r[2], r[3]); o.z = pk2(r[4], r[5]); o.w = pk2(r[6], r[7]);
;                 *(u32x4*)(pr + 9216 + c0 + q * 8) = o; }
	v_pk_mul_f32 v[12:13], v[12:13], v[60:61]
	v_rcp_f32_e32 v20, v20
	v_pk_mul_f32 v[12:13], v[46:47], v[12:13]
	v_pk_mul_f32 v[46:47], v[68:69], v[0:1] op_sel_hi:[1,0]
	v_pk_mul_f32 v[12:13], v[84:85], v[12:13]
	v_pk_mul_f32 v[14:15], v[14:15], v[46:47]
	v_pk_mul_f32 v[46:47], v[110:111], v[0:1] op_sel_hi:[1,0]
	v_pk_mul_f32 v[14:15], v[50:51], v[14:15]
	v_pk_mul_f32 v[8:9], v[8:9], v[46:47]
	v_pk_mul_f32 v[14:15], v[74:75], v[14:15]
	v_pk_mul_f32 v[8:9], v[52:53], v[8:9]
	v_rcp_f32_e32 v21, v21
	v_pk_mul_f32 v[46:47], v[70:71], v[8:9]
	v_pk_mul_f32 v[8:9], v[108:109], v[0:1] op_sel_hi:[1,0]
	v_rcp_f32_e32 v22, v22
	v_pk_mul_f32 v[8:9], v[10:11], v[8:9]
	v_cvt_pk_bf16_f32 v10, v46, v47
	v_pk_mul_f32 v[8:9], v[54:55], v[8:9]
	v_rcp_f32_e32 v23, v23
	v_pk_mul_f32 v[50:51], v[86:87], v[8:9]
	v_cvt_pk_bf16_f32 v8, v12, v13
	v_cvt_pk_bf16_f32 v9, v14, v15
	v_cvt_pk_bf16_f32 v11, v50, v51
	global_store_dwordx4 v[44:45], v[8:11], off offset:2048
	s_nop 1
	v_mov_b64_e32 v[12:13], v[200:201]
	v_mov_b64_e32 v[14:15], v[202:203]
	v_mov_b64_e32 v[8:9], v[224:225]
	v_mov_b64_e32 v[10:11], v[226:227]
	v_and_b32_e32 v4, 0xffff0000, v4
	v_mul_f32_e32 v4, 0xbfb8aa3b, v4
	v_exp_f32_e32 v4, v4
	v_pk_mul_f32 v[78:79], v[158:159], v[78:79]
	v_cmp_lt_i32_e32 vcc, s68, v32
	s_or_b64 s[14:15], vcc, s[14:15]
	v_add_f32_e32 v4, 1.0, v4
	v_rcp_f32_e32 v151, v4
	v_lshlrev_b32_e32 v4, 16, v5
	v_and_b32_e32 v5, 0xffff0000, v5
	v_mul_f32_e32 v4, 0xbfb8aa3b, v4
	v_mul_f32_e32 v5, 0xbfb8aa3b, v5
	v_exp_f32_e32 v4, v4
	v_exp_f32_e32 v5, v5
	v_add_f32_e32 v4, 1.0, v4
	v_add_f32_e32 v5, 1.0, v5
	v_rcp_f32_e32 v4, v4
	v_rcp_f32_e32 v5, v5
	v_pk_mul_f32 v[12:13], v[12:13], v[26:27]
	s_nop 0
	v_pk_mul_f32 v[12:13], v[24:25], v[12:13]
	v_pk_mul_f32 v[24:25], v[122:123], v[0:1] op_sel_hi:[1,0]
	v_pk_mul_f32 v[12:13], v[100:101], v[12:13]
	v_pk_mul_f32 v[14:15], v[14:15], v[24:25]
	v_pk_mul_f32 v[24:25], v[124:125], v[0:1] op_sel_hi:[1,0]
	v_pk_mul_f32 v[14:15], v[88:89], v[14:15]
	v_pk_mul_f32 v[8:9], v[8:9], v[24:25]
	v_pk_mul_f32 v[14:15], v[94:95], v[14:15]
	v_pk_mul_f32 v[8:9], v[90:91], v[8:9]
	s_nop 0
	v_pk_mul_f32 v[24:25], v[102:103], v[8:9]
	v_pk_mul_f32 v[8:9], v[30:31], v[0:1] op_sel_hi:[1,0]
	s_nop 0
	v_pk_mul_f32 v[8:9], v[10:11], v[8:9]
	v_cvt_pk_bf16_f32 v10, v24, v25
	v_pk_mul_f32 v[8:9], v[92:93], v[8:9]
	v_pk_mul_f32 v[24:25], v[56:57], v[0:1] op_sel_hi:[1,0]
	v_pk_mul_f32 v[26:27], v[98:99], v[8:9]
	v_cvt_pk_bf16_f32 v8, v12, v13
	v_cvt_pk_bf16_f32 v9, v14, v15
	v_cvt_pk_bf16_f32 v11, v26, v27
	global_store_dwordx4 v[44:45], v[8:11], off offset:2064
	s_nop 1
	v_mov_b64_e32 v[12:13], v[228:229]
	v_mov_b64_e32 v[14:15], v[230:231]
	v_mov_b64_e32 v[8:9], v[232:233]
	v_mov_b64_e32 v[10:11], v[234:235]
	v_pk_mul_f32 v[12:13], v[12:13], v[24:25]
	s_nop 0
	v_pk_mul_f32 v[12:13], v[96:97], v[12:13]
	s_nop 0
	v_pk_mul_f32 v[12:13], v[16:17], v[12:13]
	v_pk_mul_f32 v[16:17], v[58:59], v[0:1] op_sel_hi:[1,0]
	s_nop 0
	v_pk_mul_f32 v[14:15], v[14:15], v[16:17]
	v_pk_mul_f32 v[16:17], v[48:49], v[0:1] op_sel_hi:[1,0]
	v_pk_mul_f32 v[14:15], v[20:21], v[14:15]
	v_pk_mul_f32 v[8:9], v[8:9], v[16:17]
	v_pk_mul_f32 v[14:15], v[82:83], v[14:15]
	v_pk_mul_f32 v[8:9], v[106:107], v[8:9]
	s_nop 0
	v_pk_mul_f32 v[16:17], v[80:81], v[8:9]
	v_pk_mul_f32 v[8:9], v[76:77], v[0:1] op_sel_hi:[1,0]
	s_nop 0
	v_pk_mul_f32 v[8:9], v[10:11], v[8:9]
	v_cvt_pk_bf16_f32 v10, v16, v17
	v_pk_mul_f32 v[8:9], v[22:23], v[8:9]
	v_pk_mul_f32 v[16:17], v[18:19], v[0:1] op_sel_hi:[1,0]
	v_pk_mul_f32 v[20:21], v[146:147], v[8:9]
	v_cvt_pk_bf16_f32 v8, v12, v13
	v_cvt_pk_bf16_f32 v9, v14, v15
	v_cvt_pk_bf16_f32 v11, v20, v21
	global_store_dwordx4 v[44:45], v[8:11], off offset:2080
	s_nop 1
	v_mov_b64_e32 v[12:13], v[236:237]
	v_mov_b64_e32 v[14:15], v[238:239]
	v_mov_b64_e32 v[8:9], v[240:241]
	v_mov_b64_e32 v[10:11], v[242:243]
	v_pk_mul_f32 v[12:13], v[12:13], v[16:17]
	v_lshlrev_b32_e32 v16, 16, v1
	v_and_b32_e32 v17, 0xffff0000, v1
	v_mul_f32_e32 v1, 0xbfb8aa3b, v16
	v_exp_f32_e32 v1, v1
	v_pk_mul_f32 v[12:13], v[150:151], v[12:13]
	v_add_f32_e32 v1, 1.0, v1
	v_rcp_f32_e32 v18, v1
	v_pk_mul_f32 v[20:21], v[28:29], v[0:1] op_sel_hi:[1,0]
	v_mul_f32_e32 v1, 0xbfb8aa3b, v17
	v_exp_f32_e32 v1, v1
	v_pk_mul_f32 v[14:15], v[14:15], v[20:21]
	v_pk_mul_f32 v[12:13], v[78:79], v[12:13]
	v_pk_mul_f32 v[4:5], v[4:5], v[14:15]
	v_add_f32_e32 v1, 1.0, v1
	v_rcp_f32_e32 v19, v1
	v_lshlrev_b32_e32 v1, 16, v6
	v_mul_f32_e32 v1, 0xbfb8aa3b, v1
	v_exp_f32_e32 v1, v1
	v_pk_mul_f32 v[14:15], v[18:19], v[16:17]
	v_lshlrev_b32_e32 v16, 16, v2
	v_pk_mul_f32 v[4:5], v[14:15], v[4:5]
	v_add_f32_e32 v1, 1.0, v1
	v_rcp_f32_e32 v14, v1
	v_and_b32_e32 v1, 0xffff0000, v6
	v_mul_f32_e32 v1, 0xbfb8aa3b, v1
	v_exp_f32_e32 v1, v1
	v_and_b32_e32 v17, 0xffff0000, v2
	v_lshlrev_b32_e32 v2, 16, v3
	v_and_b32_e32 v3, 0xffff0000, v3
	v_add_f32_e32 v1, 1.0, v1
	v_rcp_f32_e32 v15, v1
	v_mul_f32_e32 v1, 0xbfb8aa3b, v16
	v_exp_f32_e32 v1, v1
	s_nop 0
	v_add_f32_e32 v1, 1.0, v1
	v_rcp_f32_e32 v18, v1
	v_pk_mul_f32 v[20:21], v[120:121], v[0:1] op_sel_hi:[1,0]
	v_mul_f32_e32 v1, 0xbfb8aa3b, v17
	v_exp_f32_e32 v1, v1
	v_pk_mul_f32 v[8:9], v[8:9], v[20:21] op_sel:[0,1] op_sel_hi:[1,0]
	v_add_f32_e32 v1, 1.0, v1
	v_rcp_f32_e32 v19, v1
	v_lshlrev_b32_e32 v1, 16, v7
	v_mul_f32_e32 v1, 0xbfb8aa3b, v1
	v_exp_f32_e32 v1, v1
	v_pk_mul_f32 v[8:9], v[14:15], v[8:9]
	v_pk_mul_f32 v[14:15], v[18:19], v[16:17]
	v_add_f32_e32 v1, 1.0, v1
	v_rcp_f32_e32 v6, v1
	v_and_b32_e32 v1, 0xffff0000, v7
	v_mul_f32_e32 v1, 0xbfb8aa3b, v1
	v_exp_f32_e32 v1, v1
	v_pk_mul_f32 v[8:9], v[14:15], v[8:9]
	v_add_f32_e32 v1, 1.0, v1
	v_rcp_f32_e32 v7, v1
	v_mul_f32_e32 v1, 0xbfb8aa3b, v2
	v_exp_f32_e32 v1, v1
	s_nop 0
	v_add_f32_e32 v1, 1.0, v1
	v_rcp_f32_e32 v14, v1
	v_pk_mul_f32 v[0:1], v[62:63], v[0:1] op_sel_hi:[1,0]
	s_nop 0
	v_pk_mul_f32 v[0:1], v[10:11], v[0:1] op_sel:[0,1] op_sel_hi:[1,0]
	s_nop 0
	v_pk_mul_f32 v[0:1], v[6:7], v[0:1]
	v_mul_f32_e32 v6, 0xbfb8aa3b, v3
	v_exp_f32_e32 v6, v6
	s_nop 0
	v_add_f32_e32 v6, 1.0, v6
	v_rcp_f32_e32 v15, v6
	s_nop 0
	v_pk_mul_f32 v[2:3], v[14:15], v[2:3]
	s_nop 0
	v_pk_mul_f32 v[6:7], v[2:3], v[0:1]
	v_cvt_pk_bf16_f32 v0, v12, v13
	v_cvt_pk_bf16_f32 v1, v4, v5
	v_cvt_pk_bf16_f32 v2, v8, v9
	v_cvt_pk_bf16_f32 v3, v6, v7
	global_store_dwordx4 v[44:45], v[0:3], off offset:2096
	s_andn2_b64 exec, exec, s[14:15]
	s_cbranch_execnz .LBB0_12

;     __device__ __forceinline__ void operator()(const f32x4 (&acc)[2][2][4][2], const pg8::Unit& u, int wr, int wc, int fr, int fq) const {
;         const int g0 = u.pm * 256 + row_off;
;         const bool isctx = g0 < CTXROWS;
;         const int b = isctx ? (g0 >> 8) : ((g0 - CTXROWS) >> 13);
;         const float* gate = modl + (size_t)(isctx ? 2 : b) * 6144 + 4096;
;         const float* xr = isctx ? xres_ctx + (size_t)g0 * D : xres_lat + (size_t)(g0 - CTXROWS) * D;
;         float* ds = isctx ? dst_ctx + (size_t)g0 * D : dst_lat + (size_t)(g0 - CTXROWS) * D;
;         const int col0 = u.pn * 256 + wc * 32 + 4 * fq;
;         f32x4 gv[2][2];
; #pragma unroll
;         for (int bj = 0; bj < 2; ++bj)
; #pragma unroll
;             for (int n = 0; n < 2; ++n) gv[bj][n] = *(const f32x4*)(gate + col0 + bj * 128 + n * 16);
; #pragma unroll
;         for (int ai = 0; ai < 2; ++ai)
; #pragma unroll
;             for (int m = 0; m < 4; ++m) { const size_t ro = (size_t)(wr * 64 + fr + ai * 128 + m * 16) * D + col0;
; #pragma unroll
;                 for (int bj = 0; bj < 2; ++bj)
; #pragma unroll
;                     for (int n = 0; n < 2; ++n) { const f32x4 xv = *(const f32x4*)(xr + ro + bj * 128 + n * 16);
;                         *(f32x4*)(ds + ro + bj * 128 + n * 16) = xv * ALPHA + gv[bj][n] * acc[ai][bj][m][n]; } }
.LBB0_326:
	s_add_u32 s22, s28, s24
	s_addc_u32 s23, s29, s25
	s_lshl_b64 s[24:25], s[26:27], 2
	v_lshl_or_b32 v176, s68, 8, v179
	s_add_u32 s24, s56, s24
	v_ashrrev_i32_e32 v177, 31, v176
	s_addc_u32 s25, s57, s25
	v_lshl_add_u64 v[132:133], v[152:153], 0, v[176:177]
	v_lshl_add_u64 v[128:129], v[176:177], 2, s[24:25]
	s_mov_b32 s17, 0x32434000
	v_lshlrev_b64 v[132:133], 2, v[132:133]
	v_add_co_u32_e32 v130, vcc, s17, v128
	v_lshl_add_u64 v[186:187], s[22:23], 0, v[132:133]
	v_addc_co_u32_e32 v131, vcc, 0, v129, vcc
	global_load_dwordx4 v[140:143], v[130:131], off
	s_mov_b64 s[24:25], 0x32434000
	v_lshl_add_u64 v[188:189], s[8:9], 0, v[132:133]
	v_lshl_add_u64 v[128:129], v[128:129], 0, s[24:25]
	global_load_dwordx4 v[136:139], v[128:129], off offset:64
	global_load_dwordx4 v[132:135], v[128:129], off offset:512
	s_nop 0
	global_load_dwordx4 v[128:131], v[128:129], off offset:576
	v_lshl_add_u64 v[194:195], v[152:153], 0, v[176:177]
	v_lshlrev_b64 v[194:195], 2, v[194:195]
	v_lshl_add_u64 v[196:197], s[22:23], 0, v[194:195]
	global_load_dwordx4 v[224:227], v[196:197], off
	global_load_dwordx4 v[228:231], v[196:197], off offset:64
	global_load_dwordx4 v[232:235], v[196:197], off offset:512
	global_load_dwordx4 v[236:239], v[196:197], off offset:576
	s_mov_b32 s68, s16
	s_mov_b32 s28, s67
	s_mov_b64 s[24:25], s[20:21]
	s_and_b64 vcc, exec, s[6:7]
	s_waitcnt vmcnt(0)
	v_lshl_add_u64 v[194:195], v[158:159], 0, v[176:177]
	v_lshlrev_b64 v[194:195], 2, v[194:195]
	v_lshl_add_u64 v[196:197], s[22:23], 0, v[194:195]
	global_load_dwordx4 v[240:243], v[196:197], off
	global_load_dwordx4 v[244:247], v[196:197], off offset:64
	global_load_dwordx4 v[248:251], v[196:197], off offset:512
	global_load_dwordx4 v[190:193], v[196:197], off offset:576
	v_pk_mul_f32 v[184:185], v[226:227], s[50:51] op_sel_hi:[1,0]
	v_pk_mul_f32 v[182:183], v[224:225], s[50:51] op_sel_hi:[1,0]
	v_pk_fma_f32 v[126:127], v[126:127], v[142:143], v[184:185]
	v_pk_fma_f32 v[124:125], v[124:125], v[140:141], v[182:183]
	global_store_dwordx4 v[188:189], v[124:127], off
	s_nop 3
	v_pk_mul_f32 v[126:127], v[230:231], s[50:51] op_sel_hi:[1,0]
	v_pk_mul_f32 v[124:125], v[228:229], s[50:51] op_sel_hi:[1,0]
	v_pk_fma_f32 v[122:123], v[122:123], v[138:139], v[126:127]
	v_pk_fma_f32 v[120:121], v[120:121], v[136:137], v[124:125]
	global_store_dwordx4 v[188:189], v[120:123], off offset:64
	s_nop 3
	v_pk_mul_f32 v[122:123], v[234:235], s[50:51] op_sel_hi:[1,0]
	v_pk_mul_f32 v[120:121], v[232:233], s[50:51] op_sel_hi:[1,0]
	v_pk_fma_f32 v[118:119], v[118:119], v[134:135], v[122:123]
	v_pk_fma_f32 v[116:117], v[116:117], v[132:133], v[120:121]
	global_store_dwordx4 v[188:189], v[116:119], off offset:512
	s_nop 3
	v_lshl_add_u64 v[120:121], v[158:159], 0, v[176:177]
	v_lshlrev_b64 v[120:121], 2, v[120:121]
	v_lshl_add_u64 v[122:123], s[22:23], 0, v[120:121]
	v_pk_mul_f32 v[118:119], v[238:239], s[50:51] op_sel_hi:[1,0]
	v_pk_mul_f32 v[116:117], v[236:237], s[50:51] op_sel_hi:[1,0]
	v_pk_fma_f32 v[110:111], v[110:111], v[130:131], v[118:119]
	v_pk_fma_f32 v[108:109], v[108:109], v[128:129], v[116:117]
	global_store_dwordx4 v[188:189], v[108:111], off offset:576
	s_nop 3
	v_lshl_add_u64 v[116:117], s[8:9], 0, v[120:121]
	s_waitcnt vmcnt(0)
	v_lshl_add_u64 v[194:195], v[160:161], 0, v[176:177]
	v_lshlrev_b64 v[194:195], 2, v[194:195]
	v_lshl_add_u64 v[196:197], s[22:23], 0, v[194:195]
	global_load_dwordx4 v[224:227], v[196:197], off
	global_load_dwordx4 v[228:231], v[196:197], off offset:64
	global_load_dwordx4 v[232:235], v[196:197], off offset:512
	global_load_dwordx4 v[236:239], v[196:197], off offset:576
	v_pk_mul_f32 v[110:111], v[242:243], s[50:51] op_sel_hi:[1,0]
	v_pk_mul_f32 v[108:109], v[240:241], s[50:51] op_sel_hi:[1,0]
	v_pk_fma_f32 v[110:111], v[114:115], v[142:143], v[110:111]
	v_pk_fma_f32 v[108:109], v[112:113], v[140:141], v[108:109]
	global_store_dwordx4 v[116:117], v[108:111], off
	s_nop 3
	v_pk_mul_f32 v[110:111], v[246:247], s[50:51] op_sel_hi:[1,0]
	v_pk_mul_f32 v[108:109], v[244:245], s[50:51] op_sel_hi:[1,0]
	v_pk_fma_f32 v[106:107], v[106:107], v[138:139], v[110:111]
	v_pk_fma_f32 v[104:105], v[104:105], v[136:137], v[108:109]
	global_store_dwordx4 v[116:117], v[104:107], off offset:64
	s_nop 3
	v_pk_mul_f32 v[106:107], v[250:251], s[50:51] op_sel_hi:[1,0]
	v_pk_mul_f32 v[104:105], v[248:249], s[50:51] op_sel_hi:[1,0]
	v_pk_fma_f32 v[102:103], v[102:103], v[134:135], v[106:107]
	v_pk_fma_f32 v[100:101], v[100:101], v[132:133], v[104:105]
	global_store_dwordx4 v[116:117], v[100:103], off offset:512
	s_nop 3
	v_lshl_add_u64 v[104:105], v[160:161], 0, v[176:177]
	v_lshlrev_b64 v[104:105], 2, v[104:105]
	v_lshl_add_u64 v[106:107], s[22:23], 0, v[104:105]
	v_pk_mul_f32 v[102:103], v[192:193], s[50:51] op_sel_hi:[1,0]
	v_pk_mul_f32 v[100:101], v[190:191], s[50:51] op_sel_hi:[1,0]
	v_pk_fma_f32 v[94:95], v[94:95], v[130:131], v[102:103]
	v_pk_fma_f32 v[92:93], v[92:93], v[128:129], v[100:101]
	global_store_dwordx4 v[116:117], v[92:95], off offset:576
	s_nop 3
	v_lshl_add_u64 v[100:101], s[8:9], 0, v[104:105]
	s_waitcnt vmcnt(0)
;     __device__ __forceinline__ void operator()(const f32x4 (&acc)[2][2][4][2], const pg8::Unit& u, int wr, int wc, int fr, int fq) const {
;     ...
;         for (int ai = 0; ai < 2; ++ai)
; #pragma unroll
;             for (int m = 0; m < 4; ++m) { const size_t ro = (size_t)(wr * 64 + fr + ai * 128 + m * 16) * D + col0;
; #pragma unroll
;                 for (int bj = 0; bj < 2; ++bj)
; #pragma unroll
;                     for (int n = 0; n < 2; ++n) { const f32x4 xv = *(const f32x4*)(xr + ro + bj * 128 + n * 16);
;                         *(f32x4*)(ds + ro + bj * 128 + n * 16) = xv * ALPHA + gv[bj][n] * acc[ai][bj][m][n]; } }
	v_lshl_add_u64 v[194:195], v[162:163], 0, v[176:177]
	v_lshlrev_b64 v[194:195], 2, v[194:195]
	v_lshl_add_u64 v[196:197], s[22:23], 0, v[194:195]
	global_load_dwordx4 v[240:243], v[196:197], off
	global_load_dwordx4 v[244:247], v[196:197], off offset:64
	global_load_dwordx4 v[248:251], v[196:197], off offset:512
	global_load_dwordx4 v[190:193], v[196:197], off offset:576
	v_pk_mul_f32 v[94:95], v[226:227], s[50:51] op_sel_hi:[1,0]
	v_pk_mul_f32 v[92:93], v[224:225], s[50:51] op_sel_hi:[1,0]
	v_pk_fma_f32 v[94:95], v[98:99], v[142:143], v[94:95]
	v_pk_fma_f32 v[92:93], v[96:97], v[140:141], v[92:93]
	global_store_dwordx4 v[100:101], v[92:95], off
	s_nop 3
	v_pk_mul_f32 v[94:95], v[230:231], s[50:51] op_sel_hi:[1,0]
	v_pk_mul_f32 v[92:93], v[228:229], s[50:51] op_sel_hi:[1,0]
	v_pk_fma_f32 v[90:91], v[90:91], v[138:139], v[94:95]
	v_pk_fma_f32 v[88:89], v[88:89], v[136:137], v[92:93]
	global_store_dwordx4 v[100:101], v[88:91], off offset:64
	s_nop 3
	v_pk_mul_f32 v[90:91], v[234:235], s[50:51] op_sel_hi:[1,0]
	v_pk_mul_f32 v[88:89], v[232:233], s[50:51] op_sel_hi:[1,0]
	v_pk_fma_f32 v[86:87], v[86:87], v[134:135], v[90:91]
	v_pk_fma_f32 v[84:85], v[84:85], v[132:133], v[88:89]
	global_store_dwordx4 v[100:101], v[84:87], off offset:512
	s_nop 3
	v_lshl_add_u64 v[88:89], v[162:163], 0, v[176:177]
	v_lshlrev_b64 v[88:89], 2, v[88:89]
	v_lshl_add_u64 v[90:91], s[22:23], 0, v[88:89]
	v_pk_mul_f32 v[86:87], v[238:239], s[50:51] op_sel_hi:[1,0]
	v_pk_mul_f32 v[84:85], v[236:237], s[50:51] op_sel_hi:[1,0]
	v_pk_fma_f32 v[78:79], v[78:79], v[130:131], v[86:87]
	v_pk_fma_f32 v[76:77], v[76:77], v[128:129], v[84:85]
	global_store_dwordx4 v[100:101], v[76:79], off offset:576
	s_nop 3
	v_lshl_add_u64 v[84:85], s[8:9], 0, v[88:89]
	s_waitcnt vmcnt(0)
	v_lshl_add_u64 v[194:195], v[164:165], 0, v[176:177]
	v_lshlrev_b64 v[194:195], 2, v[194:195]
	v_lshl_add_u64 v[196:197], s[22:23], 0, v[194:195]
	global_load_dwordx4 v[224:227], v[196:197], off
	global_load_dwordx4 v[228:231], v[196:197], off offset:64
	global_load_dwordx4 v[232:235], v[196:197], off offset:512
	global_load_dwordx4 v[236:239], v[196:197], off offset:576
	v_pk_mul_f32 v[78:79], v[242:243], s[50:51] op_sel_hi:[1,0]
	v_pk_mul_f32 v[76:77], v[240:241], s[50:51] op_sel_hi:[1,0]
	v_pk_fma_f32 v[78:79], v[82:83], v[142:143], v[78:79]
	v_pk_fma_f32 v[76:77], v[80:81], v[140:141], v[76:77]
	global_store_dwordx4 v[84:85], v[76:79], off
	s_nop 3
	v_pk_mul_f32 v[78:79], v[246:247], s[50:51] op_sel_hi:[1,0]
	v_pk_mul_f32 v[76:77], v[244:245], s[50:51] op_sel_hi:[1,0]
	v_pk_fma_f32 v[74:75], v[74:75], v[138:139], v[78:79]
	v_pk_fma_f32 v[72:73], v[72:73], v[136:137], v[76:77]
	global_store_dwordx4 v[84:85], v[72:75], off offset:64
	s_nop 3
	v_pk_mul_f32 v[74:75], v[250:251], s[50:51] op_sel_hi:[1,0]
	v_pk_mul_f32 v[72:73], v[248:249], s[50:51] op_sel_hi:[1,0]
	v_pk_fma_f32 v[70:71], v[70:71], v[134:135], v[74:75]
	v_pk_fma_f32 v[68:69], v[68:69], v[132:133], v[72:73]
	global_store_dwordx4 v[84:85], v[68:71], off offset:512
	s_nop 3
	v_lshl_add_u64 v[72:73], v[164:165], 0, v[176:177]
	v_lshlrev_b64 v[72:73], 2, v[72:73]
	v_lshl_add_u64 v[74:75], s[22:23], 0, v[72:73]
	v_pk_mul_f32 v[70:71], v[192:193], s[50:51] op_sel_hi:[1,0]
	v_pk_mul_f32 v[68:69], v[190:191], s[50:51] op_sel_hi:[1,0]
	v_pk_fma_f32 v[66:67], v[66:67], v[130:131], v[70:71]
	v_pk_fma_f32 v[64:65], v[64:65], v[128:129], v[68:69]
	global_store_dwordx4 v[84:85], v[64:67], off offset:576
	s_nop 3
	v_lshl_add_u64 v[68:69], s[8:9], 0, v[72:73]
	s_waitcnt vmcnt(0)
	v_lshl_add_u64 v[194:195], v[166:167], 0, v[176:177]
	v_lshlrev_b64 v[194:195], 2, v[194:195]
	v_lshl_add_u64 v[196:197], s[22:23], 0, v[194:195]
	global_load_dwordx4 v[240:243], v[196:197], off
	global_load_dwordx4 v[244:247], v[196:197], off offset:64
	global_load_dwordx4 v[248:251], v[196:197], off offset:512
	global_load_dwordx4 v[190:193], v[196:197], off offset:576
	v_pk_mul_f32 v[66:67], v[226:227], s[50:51] op_sel_hi:[1,0]
	v_pk_mul_f32 v[64:65], v[224:225], s[50:51] op_sel_hi:[1,0]
	v_pk_fma_f32 v[62:63], v[62:63], v[142:143], v[66:67]
	v_pk_fma_f32 v[60:61], v[60:61], v[140:141], v[64:65]
	global_store_dwordx4 v[68:69], v[60:63], off
	s_nop 3
	v_pk_mul_f32 v[62:63], v[230:231], s[50:51] op_sel_hi:[1,0]
	v_pk_mul_f32 v[60:61], v[228:229], s[50:51] op_sel_hi:[1,0]
	v_pk_fma_f32 v[58:59], v[58:59], v[138:139], v[62:63]
	v_pk_fma_f32 v[56:57], v[56:57], v[136:137], v[60:61]
	global_store_dwordx4 v[68:69], v[56:59], off offset:64
	s_nop 3
	v_pk_mul_f32 v[58:59], v[234:235], s[50:51] op_sel_hi:[1,0]
	v_pk_mul_f32 v[56:57], v[232:233], s[50:51] op_sel_hi:[1,0]
	v_pk_fma_f32 v[54:55], v[54:55], v[134:135], v[58:59]
	v_pk_fma_f32 v[52:53], v[52:53], v[132:133], v[56:57]
	global_store_dwordx4 v[68:69], v[52:55], off offset:512
	s_nop 3
	v_lshl_add_u64 v[56:57], v[166:167], 0, v[176:177]
	v_lshlrev_b64 v[56:57], 2, v[56:57]
	v_lshl_add_u64 v[58:59], s[22:23], 0, v[56:57]
	v_pk_mul_f32 v[54:55], v[238:239], s[50:51] op_sel_hi:[1,0]
	v_pk_mul_f32 v[52:53], v[236:237], s[50:51] op_sel_hi:[1,0]
	v_pk_fma_f32 v[46:47], v[46:47], v[130:131], v[54:55]
	v_pk_fma_f32 v[44:45], v[44:45], v[128:129], v[52:53]
	global_store_dwordx4 v[68:69], v[44:47], off offset:576
	s_nop 3
	v_lshl_add_u64 v[52:53], s[8:9], 0, v[56:57]
	s_waitcnt vmcnt(0)
;     __device__ __forceinline__ void operator()(const f32x4 (&acc)[2][2][4][2], const pg8::Unit& u, int wr, int wc, int fr, int fq) const {
;     ...
;         for (int ai = 0; ai < 2; ++ai)
; #pragma unroll
;             for (int m = 0; m < 4; ++m) { const size_t ro = (size_t)(wr * 64 + fr + ai * 128 + m * 16) * D + col0;
; #pragma unroll
;                 for (int bj = 0; bj < 2; ++bj)
; #pragma unroll
;                     for (int n = 0; n < 2; ++n) { const f32x4 xv = *(const f32x4*)(xr + ro + bj * 128 + n * 16);
;                         *(f32x4*)(ds + ro + bj * 128 + n * 16) = xv * ALPHA + gv[bj][n] * acc[ai][bj][m][n]; } }
	v_lshl_add_u64 v[194:195], v[168:169], 0, v[176:177]
	v_lshlrev_b64 v[194:195], 2, v[194:195]
	v_lshl_add_u64 v[196:197], s[22:23], 0, v[194:195]
	global_load_dwordx4 v[224:227], v[196:197], off
	global_load_dwordx4 v[228:231], v[196:197], off offset:64
	global_load_dwordx4 v[232:235], v[196:197], off offset:512
	global_load_dwordx4 v[236:239], v[196:197], off offset:576
	v_pk_mul_f32 v[46:47], v[242:243], s[50:51] op_sel_hi:[1,0]
	v_pk_mul_f32 v[44:45], v[240:241], s[50:51] op_sel_hi:[1,0]
	v_pk_fma_f32 v[46:47], v[50:51], v[142:143], v[46:47]
	v_pk_fma_f32 v[44:45], v[48:49], v[140:141], v[44:45]
	global_store_dwordx4 v[52:53], v[44:47], off
	s_nop 3
	v_pk_mul_f32 v[46:47], v[246:247], s[50:51] op_sel_hi:[1,0]
	v_pk_mul_f32 v[44:45], v[244:245], s[50:51] op_sel_hi:[1,0]
	v_pk_fma_f32 v[42:43], v[42:43], v[138:139], v[46:47]
	v_pk_fma_f32 v[40:41], v[40:41], v[136:137], v[44:45]
	global_store_dwordx4 v[52:53], v[40:43], off offset:64
	s_nop 3
	v_pk_mul_f32 v[42:43], v[250:251], s[50:51] op_sel_hi:[1,0]
	v_pk_mul_f32 v[40:41], v[248:249], s[50:51] op_sel_hi:[1,0]
	v_pk_fma_f32 v[38:39], v[38:39], v[134:135], v[42:43]
	v_pk_fma_f32 v[36:37], v[36:37], v[132:133], v[40:41]
	global_store_dwordx4 v[52:53], v[36:39], off offset:512
	s_nop 3
	v_lshl_add_u64 v[40:41], v[168:169], 0, v[176:177]
	v_lshlrev_b64 v[40:41], 2, v[40:41]
	v_lshl_add_u64 v[42:43], s[22:23], 0, v[40:41]
	v_pk_mul_f32 v[38:39], v[192:193], s[50:51] op_sel_hi:[1,0]
	v_pk_mul_f32 v[36:37], v[190:191], s[50:51] op_sel_hi:[1,0]
	v_pk_fma_f32 v[30:31], v[30:31], v[130:131], v[38:39]
	v_pk_fma_f32 v[28:29], v[28:29], v[128:129], v[36:37]
	global_store_dwordx4 v[52:53], v[28:31], off offset:576
	s_nop 3
	v_lshl_add_u64 v[36:37], s[8:9], 0, v[40:41]
	s_waitcnt vmcnt(0)
	v_lshl_add_u64 v[194:195], v[170:171], 0, v[176:177]
	v_lshlrev_b64 v[194:195], 2, v[194:195]
	v_lshl_add_u64 v[196:197], s[22:23], 0, v[194:195]
	global_load_dwordx4 v[240:243], v[196:197], off
	global_load_dwordx4 v[244:247], v[196:197], off offset:64
	global_load_dwordx4 v[248:251], v[196:197], off offset:512
	global_load_dwordx4 v[190:193], v[196:197], off offset:576
	v_pk_mul_f32 v[30:31], v[226:227], s[50:51] op_sel_hi:[1,0]
	v_pk_mul_f32 v[28:29], v[224:225], s[50:51] op_sel_hi:[1,0]
	v_pk_fma_f32 v[30:31], v[34:35], v[142:143], v[30:31]
	v_pk_fma_f32 v[28:29], v[32:33], v[140:141], v[28:29]
	global_store_dwordx4 v[36:37], v[28:31], off
	s_nop 3
	v_pk_mul_f32 v[30:31], v[230:231], s[50:51] op_sel_hi:[1,0]
	v_pk_mul_f32 v[28:29], v[228:229], s[50:51] op_sel_hi:[1,0]
	v_pk_fma_f32 v[26:27], v[26:27], v[138:139], v[30:31]
	v_pk_fma_f32 v[24:25], v[24:25], v[136:137], v[28:29]
	global_store_dwordx4 v[36:37], v[24:27], off offset:64
	s_nop 3
	v_pk_mul_f32 v[26:27], v[234:235], s[50:51] op_sel_hi:[1,0]
	v_pk_mul_f32 v[24:25], v[232:233], s[50:51] op_sel_hi:[1,0]
	v_pk_fma_f32 v[22:23], v[22:23], v[134:135], v[26:27]
	v_pk_fma_f32 v[20:21], v[20:21], v[132:133], v[24:25]
	global_store_dwordx4 v[36:37], v[20:23], off offset:512
	s_nop 3
	v_lshl_add_u64 v[24:25], v[170:171], 0, v[176:177]
	v_lshlrev_b64 v[24:25], 2, v[24:25]
	v_lshl_add_u64 v[26:27], s[22:23], 0, v[24:25]
	s_mov_b64 s[22:23], s[18:19]
	v_pk_mul_f32 v[22:23], v[238:239], s[50:51] op_sel_hi:[1,0]
	v_pk_mul_f32 v[20:21], v[236:237], s[50:51] op_sel_hi:[1,0]
	v_pk_fma_f32 v[14:15], v[14:15], v[130:131], v[22:23]
	v_pk_fma_f32 v[12:13], v[12:13], v[128:129], v[20:21]
	global_store_dwordx4 v[36:37], v[12:15], off offset:576
	s_nop 3
	v_lshl_add_u64 v[20:21], s[8:9], 0, v[24:25]
	s_waitcnt vmcnt(0)
	v_pk_mul_f32 v[14:15], v[242:243], s[50:51] op_sel_hi:[1,0]
	v_pk_mul_f32 v[12:13], v[240:241], s[50:51] op_sel_hi:[1,0]
	v_pk_fma_f32 v[14:15], v[18:19], v[142:143], v[14:15]
	v_pk_fma_f32 v[12:13], v[16:17], v[140:141], v[12:13]
	global_store_dwordx4 v[20:21], v[12:15], off
	s_nop 3
	v_pk_mul_f32 v[14:15], v[246:247], s[50:51] op_sel_hi:[1,0]
	v_pk_mul_f32 v[12:13], v[244:245], s[50:51] op_sel_hi:[1,0]
	v_pk_fma_f32 v[10:11], v[10:11], v[138:139], v[14:15]
	v_pk_fma_f32 v[8:9], v[8:9], v[136:137], v[12:13]
	global_store_dwordx4 v[20:21], v[8:11], off offset:64
	s_nop 3
	v_pk_mul_f32 v[10:11], v[250:251], s[50:51] op_sel_hi:[1,0]
	v_pk_mul_f32 v[8:9], v[248:249], s[50:51] op_sel_hi:[1,0]
	v_pk_fma_f32 v[6:7], v[6:7], v[134:135], v[10:11]
	v_pk_fma_f32 v[4:5], v[4:5], v[132:133], v[8:9]
	global_store_dwordx4 v[20:21], v[4:7], off offset:512
	s_nop 3
	v_pk_mul_f32 v[6:7], v[192:193], s[50:51] op_sel_hi:[1,0]
	v_pk_mul_f32 v[4:5], v[190:191], s[50:51] op_sel_hi:[1,0]
	v_pk_fma_f32 v[2:3], v[2:3], v[130:131], v[6:7]
	v_pk_fma_f32 v[0:1], v[0:1], v[128:129], v[4:5]
	global_store_dwordx4 v[20:21], v[0:3], off offset:576
	s_nop 3
	s_cbranch_vccnz .LBB0_337
